# GLA stage 1: decay-projection weight rows kept in registers across a workgroup's units with the same head (28 of 34 loads skipped), block rescheduled with all loads issued first
# speedup vs baseline: 1.0062x; 1.0062x over previous
; #define LAS __attribute__((address_space(3)))
; DI int crow(int reg, int hi) { return (reg & 3) + 8 * (reg >> 2) + 4 * hi; }
; #define MFMA32(a, b, c) __builtin_amdgcn_mfma_f32_32x32x16_bf16((a), (b), (c), 0, 0, 0)
; DI void gla_stage1(const Ctx& c0, int layer, int unit, LAS unsigned char* lds) {
;     ...
;     const int bh = unit >> 6, n = unit & 63, b = bh >> 2, h = bh & 3;
;     const size_t row0 = (size_t)b * SEQ + n * 64;
;     LAS float* LA = (LAS float*)(lds + G1_LA); LAS float* PART = (LAS float*)(lds + G1_PART);
;     const bf16* gq = (const bf16*)(c.ws + O_GQ); const bf16* gk = (const bf16*)(c.ws + O_GK); const bf16* gv = (const bf16*)(c.ws + O_GV);
;     const bf16* misc = (const bf16*)(c.ws + O_MISC);
;     const float* Wa = c.a->in[I_GWA] + (size_t)layer * 16 * 256 + h * 64; const float* ba = c.a->in[I_GBA] + (size_t)layer * 256 + h * 64;
;     const int cc = tid >> 3, ch = tid & 7;
;     ...
;             if (jb <= cb) {
; #pragma unroll
;                 for (int s = 0; s < 4; ++s) { const bf16x8 a = *(const LAS bf16x8*)(kb + s * 2048 + jb * 512); x = MFMA32(a, qf[s], x); }
; #pragma unroll
;                 for (int rg = 0; rg < 16; ++rg) { const int j = 32 * jb + crow(rg, hi); if (j > cl) x[rg] = 0.f; }
.LBB0_390:
	v_writelane_b32 v250, s90, 15
	s_cmp_lt_i32 s9, 1
	v_lshrrev_b32_e32 v188, 2, v151
	v_writelane_b32 v250, s91, 16
	v_writelane_b32 v250, s78, 17
	v_writelane_b32 v250, s80, 18
	v_lshlrev_b32_e32 v187, 1, v151
	s_nop 0
	v_writelane_b32 v250, s81, 19
	v_writelane_b32 v250, s72, 20
	s_nop 1
	v_writelane_b32 v250, s73, 21
	v_writelane_b32 v250, s74, 22
	s_nop 1
	v_writelane_b32 v250, s75, 23
	v_writelane_b32 v250, s82, 24
	v_writelane_b32 v250, s92, 25
	s_nop 1
	v_writelane_b32 v250, s93, 26
	s_cbranch_scc1 .LBB0_421
	s_bfe_u32 s8, s82, 0x10006
	s_lshl_b32 s72, s8, 5
	v_lshlrev_b32_e32 v2, 2, v153
	v_or_b32_e32 v1, s72, v152
	v_or_b32_e32 v6, 32, v2
	v_cmp_gt_u32_e64 s[4:5], v6, v1
	v_cmp_lt_u32_e64 s[6:7], v6, v1
	v_or_b32_e32 v6, 34, v2
	v_cmp_gt_u32_e64 s[10:11], v6, v1
	v_or_b32_e32 v6, 35, v2
	v_cmp_gt_u32_e64 s[12:13], v6, v1
	v_or_b32_e32 v6, 40, v2
	v_cmp_gt_u32_e64 s[14:15], v6, v1
	v_or_b32_e32 v6, 41, v2
	v_cmp_gt_u32_e64 s[16:17], v6, v1
	v_or_b32_e32 v6, 42, v2
	v_cmp_gt_u32_e64 s[18:19], v6, v1
	v_or_b32_e32 v6, 43, v2
	v_cmp_gt_u32_e64 s[20:21], v6, v1
	v_or_b32_e32 v6, 48, v2
	v_cmp_gt_u32_e64 s[22:23], v6, v1
	v_or_b32_e32 v6, 49, v2
	v_cmp_gt_u32_e64 s[24:25], v6, v1
	v_or_b32_e32 v6, 50, v2
	v_cmp_gt_u32_e64 s[26:27], v6, v1
	v_or_b32_e32 v6, 51, v2
	v_cmp_gt_u32_e64 s[28:29], v6, v1
	v_or_b32_e32 v6, 56, v2
	v_cmp_gt_u32_e64 s[30:31], v6, v1
	v_or_b32_e32 v6, 57, v2
	v_cmp_gt_u32_e64 s[34:35], v6, v1
	v_or_b32_e32 v6, 58, v2
	v_cmp_gt_u32_e64 s[36:37], v6, v1
	v_or_b32_e32 v6, 59, v2
	v_cmp_gt_u32_e64 s[38:39], v6, v1
	v_or_b32_e32 v6, 27, v2
	v_cmp_gt_u32_e64 s[40:41], v6, v1
	v_or_b32_e32 v6, 26, v2
	v_cmp_gt_u32_e64 s[42:43], v6, v1
	v_or_b32_e32 v6, 25, v2
	v_cmp_gt_u32_e64 s[44:45], v6, v1
	v_or_b32_e32 v6, 24, v2
	v_cmp_gt_u32_e64 s[46:47], v6, v1
	v_or_b32_e32 v6, 19, v2
	v_cmp_gt_u32_e64 s[48:49], v6, v1
	v_or_b32_e32 v6, 18, v2
	v_cmp_gt_u32_e64 s[50:51], v6, v1
	v_or_b32_e32 v6, 17, v2
	v_cmp_gt_u32_e64 s[52:53], v6, v1
	v_or_b32_e32 v6, 16, v2
	s_lshl_b32 s0, s78, 1
	v_cmp_gt_u32_e64 s[54:55], v6, v1
	v_or_b32_e32 v6, 11, v2
	s_bitcmp1_b32 s82, 6
	v_cmp_gt_u32_e64 s[56:57], v6, v1
	v_or_b32_e32 v6, 10, v2
	s_cselect_b64 s[2:3], -1, 0
	v_cmp_gt_u32_e64 s[58:59], v6, v1
	v_or_b32_e32 v6, 9, v2
	s_lshr_b32 s73, s82, 7
	v_cmp_gt_u32_e64 s[60:61], v6, v1
	v_or_b32_e32 v6, 8, v2
	s_lshl_b32 s33, s73, 12
	v_or_b32_e32 v46, s72, v2
	s_lshl_b32 s88, s73, 5
	s_mov_b64 s[72:73], s[90:91]
	v_cmp_gt_u32_e64 s[62:63], v6, v1
	v_or_b32_e32 v6, 3, v2
	s_load_dwordx4 s[76:79], s[72:73], 0x48
	v_cmp_gt_u32_e64 s[64:65], v6, v1
	v_or_b32_e32 v6, 2, v2
	v_lshlrev_b32_e32 v5, 4, v1
	v_cmp_gt_u32_e64 s[66:67], v6, v1
	v_cmp_lt_u32_e64 s[68:69], v2, v1
	v_cmp_gt_u32_e64 s[70:71], v2, v1
	v_and_or_b32 v1, v188, 3, v2
	v_lshlrev_b32_e32 v3, 4, v152
	v_lshl_add_u32 v4, v153, 10, 0
	v_lshlrev_b32_e32 v1, 6, v1
	v_and_b32_e32 v6, 32, v187
	v_and_b32_e32 v7, 24, v186
	s_lshl_b32 s8, s8, 12
	v_lshlrev_b32_e32 v2, 7, v46
	s_mov_b32 s1, 0
	v_or3_b32 v1, v1, v6, v7
	s_add_i32 s33, s33, 0
	s_add_i32 s75, s8, 0
	v_mov_b32_e32 v49, 0
	s_addk_i32 s0, 0x5f9
	s_movk_i32 s90, 0x3000
	s_movk_i32 s91, 0x1000
	s_movk_i32 s92, 0x2000
	s_mov_b32 s93, 0xbfb8aa3b
	s_mov_b32 s94, 0x800000
	s_mov_b32 s95, 0x3f317217
	s_mov_b32 s96, 0x7f800000
	v_mov_b32_e32 v47, 0x41b17218
	v_add_u32_e32 v52, v4, v5
	v_lshlrev_b32_e32 v50, 2, v2
	v_add_u32_e32 v53, v4, v3
	s_mov_b32 s97, 0
	s_mov_b32 s8, 0x3d800000
	s_mov_b32 s74, 0x3e000000
	v_writelane_b32 v250, s0, 27
	s_mov_b32 s101, -1
	s_branch .LBB0_393

; #define LAS __attribute__((address_space(3)))
; DI float bflo(unsigned w) { return __uint_as_float(w << 16); }
; DI float bfhi(unsigned w) { return __uint_as_float(w & 0xffff0000u); }
; DI void gla_stage1(const Ctx& c0, int layer, int unit, LAS unsigned char* lds) {
;     ...
;     const int cc = tid >> 3, ch = tid & 7;
; #pragma unroll
;     for (int it = 0; it < 2; ++it) { const int idx = tid + 512 * it, vc_ = idx & 15, c_ = idx >> 4;
;         const u32x4 v = *(const u32x4*)(gv + (row0 + c_) * 512 + h * 128 + vc_ * 8);
;         *(LAS u32x4*)(lds + G1_VI + (vc_ >> 2) * 4096 + c_ * 64 + (vc_ & 3) * 16) = v; }
;     {
;         float ga[16];
;         { const u32x4 g0 = *(const u32x4*)(misc + (row0 + cc) * 64 + 32), g1 = *(const u32x4*)(misc + (row0 + cc) * 64 + 40);
;           ga[0] = bflo(g0.x); ga[1] = bfhi(g0.x); ga[2] = bflo(g0.y); ga[3] = bfhi(g0.y); ga[4] = bflo(g0.z); ga[5] = bfhi(g0.z); ga[6] = bflo(g0.w); ga[7] = bfhi(g0.w);
;           ga[8] = bflo(g1.x); ga[9] = bfhi(g1.x); ga[10] = bflo(g1.y); ga[11] = bfhi(g1.y); ga[12] = bflo(g1.z); ga[13] = bfhi(g1.z); ga[14] = bflo(g1.w); ga[15] = bfhi(g1.w); }
;         f32x4 a0 = *(const f32x4*)(ba + 8 * ch), a1 = *(const f32x4*)(ba + 8 * ch + 4);
;         const float* wap = Wa + 8 * ch; asm volatile("" : "+v"(wap));
; #pragma unroll
;         for (int rr = 0; rr < 16; ++rr) { const f32x4 w0 = *(const f32x4*)(wap + rr * 256), w1 = *(const f32x4*)(wap + rr * 256 + 4); a0 += w0 * ga[rr]; a1 += w1 * ga[rr]; }
.LBB0_400:
	s_bfe_u32 s100, s80, 0x20006
	s_cmp_eq_u32 s100, s101
	s_mov_b32 s101, s100
	s_cbranch_scc1 .Lg1b_l0
	s_mov_b64 s[98:99], 0x1000
	s_mov_b64 s[82:83], s[86:87]
	s_mov_b64 vcc, 0x1b500000
	v_mov_b32_e32 v86, v151
	v_add_u32_e32 v94, 0x200, v86
	v_ashrrev_i32_e32 v78, 4, v94
	v_ashrrev_i32_e32 v79, 31, v78
	v_and_b32_e32 v102, 7, v86
	s_mov_b64 s[72:73], s[84:85]
	s_ashr_i32 s72, s80, 8
	s_ashr_i32 s73, s72, 31
	v_and_b32_e32 v88, 15, v86
	v_lshlrev_b32_e32 v48, 4, v88
	v_lshlrev_b32_e32 v3, 4, v86
	v_ashrrev_i32_e32 v8, 4, v86
	v_ashrrev_i32_e32 v9, 31, v8
	v_and_b32_e32 v11, 48, v3
	s_lshl_b32 s0, s80, 6
	s_bfe_u32 s89, s80, 0x20006
	s_lshl_b64 s[84:85], s[72:73], 12
	s_and_b32 s0, s0, 0xfc0
	s_or_b32 s84, s84, s0
	v_lshl_add_u64 v[68:69], s[84:85], 0, v[78:79]
	v_lshlrev_b64 v[76:77], 10, v[68:69]
	s_lshl_b32 s0, s89, 8
	s_add_u32 s72, s82, s0
	s_addc_u32 s73, s83, 0
	v_lshl_add_u64 v[100:101], s[72:73], 0, v[48:49]
	v_lshlrev_b32_e32 v48, 5, v102
	s_mov_b64 s[72:73], 0xf500000
	v_lshl_add_u64 v[6:7], v[100:101], 0, s[72:73]
	v_lshl_add_u64 v[74:75], v[6:7], 0, v[76:77]
	global_load_dwordx4 v[228:231], v[74:75], off
	s_add_u32 s72, s76, s0
	s_addc_u32 s73, s77, 0
	v_lshl_add_u64 v[24:25], s[72:73], 0, v[48:49]
	global_load_dwordx4 v[200:203], v[24:25], off offset:16
	global_load_dwordx4 v[204:207], v[24:25], off
	global_load_dwordx4 v[146:149], v[24:25], off offset:1040
	global_load_dwordx4 v[220:223], v[24:25], off offset:1024
	global_load_dwordx4 v[224:227], v[24:25], off offset:2064
	global_load_dwordx4 v[236:239], v[24:25], off offset:2048
	global_load_dwordx4 v[240:243], v[24:25], off offset:3088
	global_load_dwordx4 v[72:75], v[24:25], off offset:3072
	s_add_u32 s86, s78, s0
	s_addc_u32 s87, s79, 0
	global_load_dwordx4 v[208:211], v48, s[86:87]
	global_load_dwordx4 v[212:215], v48, s[86:87] offset:16
	v_lshl_add_u64 v[244:245], v[24:25], 0, s[98:99]
	global_load_dwordx4 v[168:171], v[244:245], off offset:3088
	global_load_dwordx4 v[118:121], v[244:245], off offset:3072
	global_load_dwordx4 v[114:117], v[244:245], off offset:2064
	global_load_dwordx4 v[110:113], v[244:245], off offset:2048
	global_load_dwordx4 v[106:109], v[244:245], off offset:1040
	global_load_dwordx4 v[96:99], v[244:245], off offset:1024
	global_load_dwordx4 v[68:71], v[244:245], off
	v_lshl_add_u64 v[246:247], v[244:245], 0, s[98:99]
	global_load_dwordx4 v[90:93], v[246:247], off offset:2064
	global_load_dwordx4 v[142:145], v[246:247], off offset:2048
	global_load_dwordx4 v[138:141], v[246:247], off offset:1040
	global_load_dwordx4 v[134:137], v[246:247], off offset:1024
	global_load_dwordx4 v[130:133], v[246:247], off offset:16
	global_load_dwordx4 v[126:129], v[246:247], off
	global_load_dwordx4 v[160:163], v[246:247], off offset:3088
	global_load_dwordx4 v[156:159], v[246:247], off offset:3072
	v_lshl_add_u64 v[248:249], v[246:247], 0, s[98:99]
	global_load_dwordx4 v[216:219], v[248:249], off offset:3072
	global_load_dwordx4 v[196:199], v[248:249], off offset:2064
	global_load_dwordx4 v[180:183], v[248:249], off offset:2048
	global_load_dwordx4 v[176:179], v[248:249], off offset:1040
	global_load_dwordx4 v[172:175], v[248:249], off offset:1024
	global_load_dwordx4 v[122:125], v[248:249], off offset:16
	global_load_dwordx4 v[164:167], v[248:249], off
	v_lshlrev_b32_e32 v2, 10, v86
	v_and_b32_e32 v2, 0x3000, v2
	v_add3_u32 v13, 0, v2, v11
	v_lshl_add_u64 v[2:3], s[84:85], 0, v[8:9]
	v_lshlrev_b64 v[2:3], 10, v[2:3]
	v_lshl_add_u64 v[2:3], v[6:7], 0, v[2:3]
	global_load_dwordx4 v[82:85], v[2:3], off
	v_lshl_add_u32 v6, v78, 6, v13
	global_load_dwordx4 v[76:79], v[244:245], off offset:16
	v_lshl_add_u32 v8, v8, 6, v13
	s_waitcnt vmcnt(1)
	ds_write_b128 v8, v[82:85] offset:43264
	ds_write_b128 v6, v[228:231] offset:43264
	v_ashrrev_i32_e32 v12, 3, v86
	v_ashrrev_i32_e32 v13, 31, v12
	v_lshl_add_u64 v[2:3], s[84:85], 0, v[12:13]
	v_lshlrev_b64 v[4:5], 7, v[2:3]
	v_lshl_add_u64 v[4:5], s[82:83], 0, v[4:5]
	v_lshl_add_u64 v[8:9], v[4:5], 0, vcc
	global_load_dwordx4 v[4:7], v[8:9], off offset:64
	global_load_dwordx4 v[232:235], v[8:9], off offset:80
	s_waitcnt vmcnt(0)
	v_and_b32_e32 v20, 0xffff0000, v232
	v_lshlrev_b32_e32 v18, 16, v233
	v_lshlrev_b32_e32 v22, 16, v232
	v_and_b32_e32 v26, 0xffff0000, v7
	v_lshlrev_b32_e32 v28, 16, v7
	v_and_b32_e32 v30, 0xffff0000, v6
	v_lshlrev_b32_e32 v66, 16, v6
	v_and_b32_e32 v64, 0xffff0000, v5
	v_lshlrev_b32_e32 v62, 16, v5
	v_and_b32_e32 v60, 0xffff0000, v4
	v_lshlrev_b32_e32 v58, 16, v4
	v_pk_fma_f32 v[54:55], v[58:59], v[200:201], v[212:213] op_sel_hi:[0,1,1]
	v_pk_fma_f32 v[54:55], v[60:61], v[146:147], v[54:55] op_sel_hi:[0,1,1]
	v_pk_fma_f32 v[54:55], v[62:63], v[224:225], v[54:55] op_sel_hi:[0,1,1]
	v_pk_fma_f32 v[54:55], v[64:65], v[240:241], v[54:55] op_sel_hi:[0,1,1]
	v_pk_fma_f32 v[54:55], v[66:67], v[76:77], v[54:55] op_sel_hi:[0,1,1]
	v_pk_fma_f32 v[56:57], v[58:59], v[202:203], v[214:215] op_sel_hi:[0,1,1]
	v_pk_fma_f32 v[56:57], v[60:61], v[148:149], v[56:57] op_sel_hi:[0,1,1]
	v_pk_fma_f32 v[56:57], v[62:63], v[226:227], v[56:57] op_sel_hi:[0,1,1]
	v_pk_fma_f32 v[56:57], v[64:65], v[242:243], v[56:57] op_sel_hi:[0,1,1]
	v_pk_fma_f32 v[56:57], v[66:67], v[78:79], v[56:57] op_sel_hi:[0,1,1]
	v_pk_fma_f32 v[56:57], v[30:31], v[108:109], v[56:57] op_sel_hi:[0,1,1]
	v_pk_fma_f32 v[40:41], v[28:29], v[116:117], v[56:57] op_sel_hi:[0,1,1]
	v_pk_fma_f32 v[40:41], v[26:27], v[170:171], v[40:41] op_sel_hi:[0,1,1]
	v_pk_fma_f32 v[42:43], v[58:59], v[204:205], v[208:209] op_sel_hi:[0,1,1]
	v_pk_fma_f32 v[42:43], v[60:61], v[220:221], v[42:43] op_sel_hi:[0,1,1]
	v_pk_fma_f32 v[42:43], v[62:63], v[236:237], v[42:43] op_sel_hi:[0,1,1]
; DI float bflo(unsigned w) { return __uint_as_float(w << 16); }
; DI float bfhi(unsigned w) { return __uint_as_float(w & 0xffff0000u); }
; DI void gla_stage1(const Ctx& c0, int layer, int unit, LAS unsigned char* lds) {
;     ...
;         { const u32x4 g0 = *(const u32x4*)(misc + (row0 + cc) * 64 + 32), g1 = *(const u32x4*)(misc + (row0 + cc) * 64 + 40);
;           ga[0] = bflo(g0.x); ga[1] = bfhi(g0.x); ga[2] = bflo(g0.y); ga[3] = bfhi(g0.y); ga[4] = bflo(g0.z); ga[5] = bfhi(g0.z); ga[6] = bflo(g0.w); ga[7] = bfhi(g0.w);
;           ga[8] = bflo(g1.x); ga[9] = bfhi(g1.x); ga[10] = bflo(g1.y); ga[11] = bfhi(g1.y); ga[12] = bflo(g1.z); ga[13] = bfhi(g1.z); ga[14] = bflo(g1.w); ga[15] = bfhi(g1.w); }
;         f32x4 a0 = *(const f32x4*)(ba + 8 * ch), a1 = *(const f32x4*)(ba + 8 * ch + 4);
;         const float* wap = Wa + 8 * ch; asm volatile("" : "+v"(wap));
; #pragma unroll
;         for (int rr = 0; rr < 16; ++rr) { const f32x4 w0 = *(const f32x4*)(wap + rr * 256), w1 = *(const f32x4*)(wap + rr * 256 + 4); a0 += w0 * ga[rr]; a1 += w1 * ga[rr]; }
; #pragma unroll
;         for (int j = 0; j < 8; ++j) { const float x = j < 4 ? a0[j & 3] : a1[j & 3];
;             const float ls = fminf(x, 0.f) - __logf(1.f + __expf(-fabsf(x)));
;             LA[cc * 65 + 8 * ch + j] = ls * (1.f / 16.f); }
	v_pk_fma_f32 v[42:43], v[64:65], v[72:73], v[42:43] op_sel_hi:[0,1,1]
	v_pk_fma_f32 v[42:43], v[66:67], v[68:69], v[42:43] op_sel_hi:[0,1,1]
	v_pk_fma_f32 v[42:43], v[30:31], v[96:97], v[42:43] op_sel_hi:[0,1,1]
	v_pk_fma_f32 v[42:43], v[28:29], v[110:111], v[42:43] op_sel_hi:[0,1,1]
	v_pk_fma_f32 v[42:43], v[26:27], v[118:119], v[42:43] op_sel_hi:[0,1,1]
	v_pk_fma_f32 v[42:43], v[22:23], v[126:127], v[42:43] op_sel_hi:[0,1,1]
	v_pk_fma_f32 v[44:45], v[58:59], v[206:207], v[210:211] op_sel_hi:[0,1,1]
	v_pk_fma_f32 v[44:45], v[60:61], v[222:223], v[44:45] op_sel_hi:[0,1,1]
	v_pk_fma_f32 v[44:45], v[62:63], v[238:239], v[44:45] op_sel_hi:[0,1,1]
	v_pk_fma_f32 v[44:45], v[64:65], v[74:75], v[44:45] op_sel_hi:[0,1,1]
	v_pk_fma_f32 v[44:45], v[66:67], v[70:71], v[44:45] op_sel_hi:[0,1,1]
	v_pk_fma_f32 v[44:45], v[30:31], v[98:99], v[44:45] op_sel_hi:[0,1,1]
	v_pk_fma_f32 v[30:31], v[30:31], v[106:107], v[54:55] op_sel_hi:[0,1,1]
	v_pk_fma_f32 v[44:45], v[28:29], v[112:113], v[44:45] op_sel_hi:[0,1,1]
	v_pk_fma_f32 v[38:39], v[28:29], v[114:115], v[30:31] op_sel_hi:[0,1,1]
	v_pk_fma_f32 v[30:31], v[26:27], v[120:121], v[44:45] op_sel_hi:[0,1,1]
	v_pk_fma_f32 v[30:31], v[22:23], v[128:129], v[30:31] op_sel_hi:[0,1,1]
	v_pk_fma_f32 v[30:31], v[20:21], v[136:137], v[30:31] op_sel_hi:[0,1,1]
	v_pk_fma_f32 v[38:39], v[26:27], v[168:169], v[38:39] op_sel_hi:[0,1,1]
	v_pk_fma_f32 v[38:39], v[22:23], v[130:131], v[38:39] op_sel_hi:[0,1,1]
	v_pk_fma_f32 v[34:35], v[20:21], v[138:139], v[38:39] op_sel_hi:[0,1,1]
	v_pk_fma_f32 v[22:23], v[22:23], v[132:133], v[40:41] op_sel_hi:[0,1,1]
	v_pk_fma_f32 v[40:41], v[20:21], v[134:135], v[42:43] op_sel_hi:[0,1,1]
	v_pk_fma_f32 v[36:37], v[20:21], v[140:141], v[22:23] op_sel_hi:[0,1,1]
	v_pk_fma_f32 v[38:39], v[18:19], v[142:143], v[40:41] op_sel_hi:[0,1,1]
	v_pk_fma_f32 v[22:23], v[18:19], v[144:145], v[30:31] op_sel_hi:[0,1,1]
	v_pk_fma_f32 v[30:31], v[18:19], v[90:91], v[34:35] op_sel_hi:[0,1,1]
	v_pk_fma_f32 v[34:35], v[18:19], v[92:93], v[36:37] op_sel_hi:[0,1,1]
	global_load_dwordx4 v[18:21], v[248:249], off offset:3088
	s_movk_i32 s0, 0x104
	v_lshl_add_u32 v33, v86, 2, 0
	v_mul_lo_u32 v13, v12, s0
	v_add3_u32 v13, 0, v13, v48
	s_movk_i32 s0, 0x820
	v_and_b32_e32 v16, 0xffff0000, v233
	v_lshlrev_b32_e32 v14, 16, v234
	v_and_b32_e32 v8, 0xffff0000, v234
	v_lshlrev_b32_e32 v4, 16, v235
	v_and_b32_e32 v6, 0xffff0000, v235
	v_lshl_add_u64 v[58:59], v[24:25], 0, s[98:99]
	v_lshl_add_u64 v[44:45], v[58:59], 0, s[98:99]
	v_lshl_add_u64 v[24:25], v[44:45], 0, s[98:99]
	v_pk_fma_f32 v[36:37], v[16:17], v[158:159], v[22:23] op_sel_hi:[0,1,1]
	v_pk_fma_f32 v[38:39], v[16:17], v[156:157], v[38:39] op_sel_hi:[0,1,1]
	v_pk_fma_f32 v[28:29], v[16:17], v[162:163], v[34:35] op_sel_hi:[0,1,1]
	v_pk_fma_f32 v[26:27], v[16:17], v[160:161], v[30:31] op_sel_hi:[0,1,1]
	v_pk_fma_f32 v[30:31], v[14:15], v[164:165], v[38:39] op_sel_hi:[0,1,1]
	v_pk_fma_f32 v[34:35], v[14:15], v[166:167], v[36:37] op_sel_hi:[0,1,1]
	v_pk_fma_f32 v[26:27], v[14:15], v[122:123], v[26:27] op_sel_hi:[0,1,1]
	v_pk_fma_f32 v[22:23], v[14:15], v[124:125], v[28:29] op_sel_hi:[0,1,1]
	v_pk_fma_f32 v[28:29], v[8:9], v[174:175], v[34:35] op_sel_hi:[0,1,1]
	v_pk_fma_f32 v[30:31], v[8:9], v[172:173], v[30:31] op_sel_hi:[0,1,1]
	v_pk_fma_f32 v[22:23], v[8:9], v[178:179], v[22:23] op_sel_hi:[0,1,1]
	v_pk_fma_f32 v[8:9], v[8:9], v[176:177], v[26:27] op_sel_hi:[0,1,1]
	v_pk_fma_f32 v[26:27], v[4:5], v[180:181], v[30:31] op_sel_hi:[0,1,1]
	v_pk_fma_f32 v[28:29], v[4:5], v[182:183], v[28:29] op_sel_hi:[0,1,1]
	v_pk_fma_f32 v[30:31], v[4:5], v[196:197], v[8:9] op_sel_hi:[0,1,1]
	v_pk_fma_f32 v[4:5], v[4:5], v[198:199], v[22:23] op_sel_hi:[0,1,1]
	v_pk_fma_f32 v[14:15], v[6:7], v[216:217], v[26:27] op_sel_hi:[0,1,1]
	v_pk_fma_f32 v[8:9], v[6:7], v[218:219], v[28:29] op_sel_hi:[0,1,1]
	v_min_f32_e32 v16, 0, v14
	v_mul_f32_e64 v14, |v14|, s93
	v_exp_f32_e32 v14, v14
	s_waitcnt vmcnt(0)
	v_pk_fma_f32 v[4:5], v[6:7], v[20:21], v[4:5] op_sel_hi:[0,1,1]
	v_pk_fma_f32 v[6:7], v[6:7], v[18:19], v[30:31] op_sel_hi:[0,1,1]
	v_mov_b32_e32 v20, 0
	v_add_f32_e32 v14, 1.0, v14
	v_cmp_gt_f32_e32 vcc, s94, v14
	v_mov_b32_e32 v21, 0
	s_nop 0
	v_cndmask_b32_e64 v17, 0, 32, vcc
	v_ldexp_f32 v14, v14, v17
	v_log_f32_e32 v14, v14
	s_nop 0
	v_mul_f32_e32 v17, 0x3f317217, v14
	v_fma_f32 v17, v14, s95, -v17
	v_fmac_f32_e32 v17, 0x3377d1cf, v14
	v_fmac_f32_e32 v17, 0x3f317217, v14
	v_cmp_lt_f32_e64 s[72:73], |v14|, s96
	s_nop 1
	v_cndmask_b32_e64 v14, v14, v17, s[72:73]
	v_cndmask_b32_e32 v17, 0, v47, vcc
	v_sub_f32_e32 v14, v14, v17
	v_min_f32_e32 v17, 0, v15
	v_mul_f32_e64 v15, |v15|, s93
	v_exp_f32_e32 v15, v15
	s_nop 0
	v_add_f32_e32 v15, 1.0, v15
	v_cmp_gt_f32_e32 vcc, s94, v15
	s_nop 1
	v_cndmask_b32_e64 v18, 0, 32, vcc
	v_ldexp_f32 v15, v15, v18
	v_log_f32_e32 v15, v15
	s_nop 0
	v_mul_f32_e32 v18, 0x3f317217, v15
	v_fma_f32 v18, v15, s95, -v18
	v_fmac_f32_e32 v18, 0x3377d1cf, v15
	v_fmac_f32_e32 v18, 0x3f317217, v15
	v_cmp_lt_f32_e64 s[72:73], |v15|, s96
	s_nop 1
	v_cndmask_b32_e64 v15, v15, v18, s[72:73]
	v_cndmask_b32_e32 v18, 0, v47, vcc
	v_sub_f32_e32 v15, v15, v18
	v_pk_add_f32 v[14:15], v[16:17], v[14:15] neg_lo:[0,1] neg_hi:[0,1]
	v_ashrrev_i32_e32 v17, 6, v86
	v_pk_mul_f32 v[14:15], v[14:15], s[8:9] op_sel_hi:[1,0]
	ds_write2_b32 v13, v14, v15 offset1:1
	v_min_f32_e32 v14, 0, v8
	v_mul_f32_e64 v8, |v8|, s93
	v_exp_f32_e32 v8, v8
	s_nop 0
	v_add_f32_e32 v8, 1.0, v8
	v_cmp_gt_f32_e32 vcc, s94, v8
	s_nop 1
	v_cndmask_b32_e64 v15, 0, 32, vcc
	v_ldexp_f32 v8, v8, v15
	v_log_f32_e32 v8, v8
	s_nop 0
	v_mul_f32_e32 v15, 0x3f317217, v8
	v_fma_f32 v15, v8, s95, -v15
; #define LAS __attribute__((address_space(3)))
; DI float bflo(unsigned w) { return __uint_as_float(w << 16); }
; DI float bfhi(unsigned w) { return __uint_as_float(w & 0xffff0000u); }
; DI void gla_stage1(const Ctx& c0, int layer, int unit, LAS unsigned char* lds) {
;     ...
;     const int cc = tid >> 3, ch = tid & 7;
; #pragma unroll
;     for (int it = 0; it < 2; ++it) { const int idx = tid + 512 * it, vc_ = idx & 15, c_ = idx >> 4;
;         const u32x4 v = *(const u32x4*)(gv + (row0 + c_) * 512 + h * 128 + vc_ * 8);
;         *(LAS u32x4*)(lds + G1_VI + (vc_ >> 2) * 4096 + c_ * 64 + (vc_ & 3) * 16) = v; }
;     {
;         float ga[16];
;         { const u32x4 g0 = *(const u32x4*)(misc + (row0 + cc) * 64 + 32), g1 = *(const u32x4*)(misc + (row0 + cc) * 64 + 40);
;           ga[0] = bflo(g0.x); ga[1] = bfhi(g0.x); ga[2] = bflo(g0.y); ga[3] = bfhi(g0.y); ga[4] = bflo(g0.z); ga[5] = bfhi(g0.z); ga[6] = bflo(g0.w); ga[7] = bfhi(g0.w);
;           ga[8] = bflo(g1.x); ga[9] = bfhi(g1.x); ga[10] = bflo(g1.y); ga[11] = bfhi(g1.y); ga[12] = bflo(g1.z); ga[13] = bfhi(g1.z); ga[14] = bflo(g1.w); ga[15] = bfhi(g1.w); }
;         f32x4 a0 = *(const f32x4*)(ba + 8 * ch), a1 = *(const f32x4*)(ba + 8 * ch + 4);
;         const float* wap = Wa + 8 * ch; asm volatile("" : "+v"(wap));
;     ...
;         for (int j = 0; j < 8; ++j) { const float x = j < 4 ? a0[j & 3] : a1[j & 3];
;             const float ls = fminf(x, 0.f) - __logf(1.f + __expf(-fabsf(x)));
;             LA[cc * 65 + 8 * ch + j] = ls * (1.f / 16.f); }
	v_fmac_f32_e32 v15, 0x3377d1cf, v8
	v_fmac_f32_e32 v15, 0x3f317217, v8
	v_cmp_lt_f32_e64 s[72:73], |v8|, s96
	s_nop 1
	v_cndmask_b32_e64 v8, v8, v15, s[72:73]
	v_cndmask_b32_e32 v15, 0, v47, vcc
	v_sub_f32_e32 v8, v8, v15
	v_min_f32_e32 v15, 0, v9
	v_mul_f32_e64 v9, |v9|, s93
	v_exp_f32_e32 v9, v9
	s_nop 0
	v_add_f32_e32 v9, 1.0, v9
	v_cmp_gt_f32_e32 vcc, s94, v9
	s_nop 1
	v_cndmask_b32_e64 v16, 0, 32, vcc
	v_ldexp_f32 v9, v9, v16
	v_log_f32_e32 v9, v9
	s_nop 0
	v_mul_f32_e32 v16, 0x3f317217, v9
	v_fma_f32 v16, v9, s95, -v16
	v_fmac_f32_e32 v16, 0x3377d1cf, v9
	v_fmac_f32_e32 v16, 0x3f317217, v9
	v_cmp_lt_f32_e64 s[72:73], |v9|, s96
	s_nop 1
	v_cndmask_b32_e64 v9, v9, v16, s[72:73]
	v_cndmask_b32_e32 v16, 0, v47, vcc
	v_sub_f32_e32 v9, v9, v16
	v_pk_add_f32 v[8:9], v[14:15], v[8:9] neg_lo:[0,1] neg_hi:[0,1]
	v_pk_mul_f32 v[8:9], v[8:9], s[8:9] op_sel_hi:[1,0]
	ds_write2_b32 v13, v8, v9 offset0:2 offset1:3
	v_min_f32_e32 v8, 0, v6
	v_mul_f32_e64 v6, |v6|, s93
	v_exp_f32_e32 v6, v6
	s_nop 0
	v_add_f32_e32 v6, 1.0, v6
	v_cmp_gt_f32_e32 vcc, s94, v6
	s_nop 1
	v_cndmask_b32_e64 v9, 0, 32, vcc
	v_ldexp_f32 v6, v6, v9
	v_log_f32_e32 v6, v6
	s_nop 0
	v_mul_f32_e32 v9, 0x3f317217, v6
	v_fma_f32 v9, v6, s95, -v9
	v_fmac_f32_e32 v9, 0x3377d1cf, v6
	v_fmac_f32_e32 v9, 0x3f317217, v6
	v_cmp_lt_f32_e64 s[72:73], |v6|, s96
	s_nop 1
	v_cndmask_b32_e64 v6, v6, v9, s[72:73]
	v_cndmask_b32_e32 v9, 0, v47, vcc
	v_sub_f32_e32 v6, v6, v9
	v_min_f32_e32 v9, 0, v7
	v_mul_f32_e64 v7, |v7|, s93
	v_exp_f32_e32 v7, v7
	s_nop 0
	v_add_f32_e32 v7, 1.0, v7
	v_cmp_gt_f32_e32 vcc, s94, v7
	s_nop 1
	v_cndmask_b32_e64 v14, 0, 32, vcc
	v_ldexp_f32 v7, v7, v14
	v_log_f32_e32 v7, v7
	s_nop 0
	v_mul_f32_e32 v14, 0x3f317217, v7
	v_fma_f32 v14, v7, s95, -v14
	v_fmac_f32_e32 v14, 0x3377d1cf, v7
	v_fmac_f32_e32 v14, 0x3f317217, v7
	v_cmp_lt_f32_e64 s[72:73], |v7|, s96
	s_nop 1
	v_cndmask_b32_e64 v7, v7, v14, s[72:73]
	v_cndmask_b32_e32 v14, 0, v47, vcc
	v_sub_f32_e32 v7, v7, v14
	v_pk_add_f32 v[6:7], v[8:9], v[6:7] neg_lo:[0,1] neg_hi:[0,1]
	v_pk_mul_f32 v[6:7], v[6:7], s[8:9] op_sel_hi:[1,0]
	ds_write2_b32 v13, v6, v7 offset0:4 offset1:5
	v_min_f32_e32 v6, 0, v4
	v_mul_f32_e64 v4, |v4|, s93
	v_exp_f32_e32 v4, v4
	s_nop 0
	v_add_f32_e32 v4, 1.0, v4
	v_cmp_gt_f32_e32 vcc, s94, v4
	s_nop 1
	v_cndmask_b32_e64 v7, 0, 32, vcc
	v_ldexp_f32 v4, v4, v7
	v_log_f32_e32 v4, v4
	s_nop 0
	v_mul_f32_e32 v7, 0x3f317217, v4
	v_fma_f32 v7, v4, s95, -v7
	v_fmac_f32_e32 v7, 0x3377d1cf, v4
	v_fmac_f32_e32 v7, 0x3f317217, v4
	v_cmp_lt_f32_e64 s[72:73], |v4|, s96
	s_nop 1
	v_cndmask_b32_e64 v4, v4, v7, s[72:73]
	v_cndmask_b32_e32 v7, 0, v47, vcc
	v_sub_f32_e32 v4, v4, v7
	v_min_f32_e32 v7, 0, v5
	v_mul_f32_e64 v5, |v5|, s93
	v_exp_f32_e32 v5, v5
	s_nop 0
	v_add_f32_e32 v5, 1.0, v5
	v_cmp_gt_f32_e32 vcc, s94, v5
	s_nop 1
	v_cndmask_b32_e64 v8, 0, 32, vcc
	v_ldexp_f32 v5, v5, v8
	v_log_f32_e32 v5, v5
	s_nop 0
	v_mul_f32_e32 v8, 0x3f317217, v5
	v_fma_f32 v8, v5, s95, -v8
	v_fmac_f32_e32 v8, 0x3377d1cf, v5
	v_fmac_f32_e32 v8, 0x3f317217, v5
	v_cmp_lt_f32_e64 s[72:73], |v5|, s96
	s_nop 1
	v_cndmask_b32_e64 v5, v5, v8, s[72:73]
	v_cndmask_b32_e32 v8, 0, v47, vcc
	v_sub_f32_e32 v5, v5, v8
	v_pk_add_f32 v[4:5], v[6:7], v[4:5] neg_lo:[0,1] neg_hi:[0,1]
	v_cmp_lt_i32_e32 vcc, 0, v17
	v_pk_mul_f32 v[4:5], v[4:5], s[8:9] op_sel_hi:[1,0]
	ds_write2_b32 v13, v4, v5 offset0:6 offset1:7
	v_and_b32_e32 v4, 63, v86
	v_lshl_add_u32 v14, v4, 2, 0
	v_mul_lo_u32 v4, v17, s0
	v_add_u32_e32 v4, v14, v4
	v_mov_b32_e32 v10, v86
	v_mov_b32_e32 v80, v94
	v_mov_b32_e32 v32, v102
	s_waitcnt vmcnt(0) lgkmcnt(0)
	s_branch .Lg1j_l0
.Lg1b_l0:
	s_mov_b64 s[98:99], 0x1000
	s_mov_b64 s[82:83], s[86:87]
	s_mov_b64 vcc, 0x1b500000
	v_mov_b32_e32 v86, v151
	v_add_u32_e32 v94, 0x200, v86
	v_ashrrev_i32_e32 v78, 4, v94
	v_ashrrev_i32_e32 v79, 31, v78
	v_and_b32_e32 v102, 7, v86
	s_mov_b64 s[72:73], s[84:85]
	s_ashr_i32 s72, s80, 8
	s_ashr_i32 s73, s72, 31
	v_and_b32_e32 v88, 15, v86
	v_lshlrev_b32_e32 v48, 4, v88
	v_lshlrev_b32_e32 v3, 4, v86
	v_ashrrev_i32_e32 v8, 4, v86
	v_ashrrev_i32_e32 v9, 31, v8
	v_and_b32_e32 v11, 48, v3
	s_lshl_b32 s0, s80, 6
	s_bfe_u32 s89, s80, 0x20006
	s_lshl_b64 s[84:85], s[72:73], 12
	s_and_b32 s0, s0, 0xfc0
	s_or_b32 s84, s84, s0
	v_lshl_add_u64 v[68:69], s[84:85], 0, v[78:79]
	v_lshlrev_b64 v[76:77], 10, v[68:69]
	s_lshl_b32 s0, s89, 8
	s_add_u32 s72, s82, s0
	s_addc_u32 s73, s83, 0
	v_lshl_add_u64 v[100:101], s[72:73], 0, v[48:49]
	v_lshlrev_b32_e32 v48, 5, v102
	s_mov_b64 s[72:73], 0xf500000
	v_lshl_add_u64 v[6:7], v[100:101], 0, s[72:73]
	v_lshl_add_u64 v[74:75], v[6:7], 0, v[76:77]
	global_load_dwordx4 v[228:231], v[74:75], off
	s_add_u32 s72, s76, s0
	s_addc_u32 s73, s77, 0
	v_lshl_add_u64 v[24:25], s[72:73], 0, v[48:49]
	global_load_dwordx4 v[236:239], v[24:25], off offset:2048
	global_load_dwordx4 v[240:243], v[24:25], off offset:3088
	global_load_dwordx4 v[72:75], v[24:25], off offset:3072
	s_add_u32 s86, s78, s0
	s_addc_u32 s87, s79, 0
	v_lshl_add_u64 v[244:245], v[24:25], 0, s[98:99]
	global_load_dwordx4 v[68:71], v[244:245], off
	v_lshl_add_u64 v[246:247], v[244:245], 0, s[98:99]
	v_lshl_add_u64 v[248:249], v[246:247], 0, s[98:99]
	v_lshlrev_b32_e32 v2, 10, v86
	v_and_b32_e32 v2, 0x3000, v2
	v_add3_u32 v13, 0, v2, v11
	v_lshl_add_u64 v[2:3], s[84:85], 0, v[8:9]
	v_lshlrev_b64 v[2:3], 10, v[2:3]
	v_lshl_add_u64 v[2:3], v[6:7], 0, v[2:3]
	global_load_dwordx4 v[82:85], v[2:3], off
	v_lshl_add_u32 v6, v78, 6, v13
	global_load_dwordx4 v[76:79], v[244:245], off offset:16
	v_lshl_add_u32 v8, v8, 6, v13
	s_waitcnt vmcnt(1)
; #define LAS __attribute__((address_space(3)))
; DI float bflo(unsigned w) { return __uint_as_float(w << 16); }
; DI float bfhi(unsigned w) { return __uint_as_float(w & 0xffff0000u); }
; DI void gla_stage1(const Ctx& c0, int layer, int unit, LAS unsigned char* lds) {
;     ...
;     for (int it = 0; it < 2; ++it) { const int idx = tid + 512 * it, vc_ = idx & 15, c_ = idx >> 4;
;         const u32x4 v = *(const u32x4*)(gv + (row0 + c_) * 512 + h * 128 + vc_ * 8);
;         *(LAS u32x4*)(lds + G1_VI + (vc_ >> 2) * 4096 + c_ * 64 + (vc_ & 3) * 16) = v; }
;     {
;         float ga[16];
;         { const u32x4 g0 = *(const u32x4*)(misc + (row0 + cc) * 64 + 32), g1 = *(const u32x4*)(misc + (row0 + cc) * 64 + 40);
;           ga[0] = bflo(g0.x); ga[1] = bfhi(g0.x); ga[2] = bflo(g0.y); ga[3] = bfhi(g0.y); ga[4] = bflo(g0.z); ga[5] = bfhi(g0.z); ga[6] = bflo(g0.w); ga[7] = bfhi(g0.w);
;           ga[8] = bflo(g1.x); ga[9] = bfhi(g1.x); ga[10] = bflo(g1.y); ga[11] = bfhi(g1.y); ga[12] = bflo(g1.z); ga[13] = bfhi(g1.z); ga[14] = bflo(g1.w); ga[15] = bfhi(g1.w); }
;         f32x4 a0 = *(const f32x4*)(ba + 8 * ch), a1 = *(const f32x4*)(ba + 8 * ch + 4);
;         const float* wap = Wa + 8 * ch; asm volatile("" : "+v"(wap));
; #pragma unroll
;         for (int rr = 0; rr < 16; ++rr) { const f32x4 w0 = *(const f32x4*)(wap + rr * 256), w1 = *(const f32x4*)(wap + rr * 256 + 4); a0 += w0 * ga[rr]; a1 += w1 * ga[rr]; }
	ds_write_b128 v8, v[82:85] offset:43264
	ds_write_b128 v6, v[228:231] offset:43264
	v_ashrrev_i32_e32 v12, 3, v86
	v_ashrrev_i32_e32 v13, 31, v12
	v_lshl_add_u64 v[2:3], s[84:85], 0, v[12:13]
	v_lshlrev_b64 v[4:5], 7, v[2:3]
	v_lshl_add_u64 v[4:5], s[82:83], 0, v[4:5]
	v_lshl_add_u64 v[8:9], v[4:5], 0, vcc
	global_load_dwordx4 v[4:7], v[8:9], off offset:64
	global_load_dwordx4 v[232:235], v[8:9], off offset:80
	s_waitcnt vmcnt(0)
	v_and_b32_e32 v20, 0xffff0000, v232
	v_lshlrev_b32_e32 v18, 16, v233
	v_lshlrev_b32_e32 v22, 16, v232
	v_and_b32_e32 v26, 0xffff0000, v7
	v_lshlrev_b32_e32 v28, 16, v7
	v_and_b32_e32 v30, 0xffff0000, v6
	v_lshlrev_b32_e32 v66, 16, v6
	v_and_b32_e32 v64, 0xffff0000, v5
	v_lshlrev_b32_e32 v62, 16, v5
	v_and_b32_e32 v60, 0xffff0000, v4
	v_lshlrev_b32_e32 v58, 16, v4
	v_pk_fma_f32 v[54:55], v[58:59], v[200:201], v[212:213] op_sel_hi:[0,1,1]
	v_pk_fma_f32 v[54:55], v[60:61], v[146:147], v[54:55] op_sel_hi:[0,1,1]
	v_pk_fma_f32 v[54:55], v[62:63], v[224:225], v[54:55] op_sel_hi:[0,1,1]
	v_pk_fma_f32 v[54:55], v[64:65], v[240:241], v[54:55] op_sel_hi:[0,1,1]
	v_pk_fma_f32 v[54:55], v[66:67], v[76:77], v[54:55] op_sel_hi:[0,1,1]
	v_pk_fma_f32 v[56:57], v[58:59], v[202:203], v[214:215] op_sel_hi:[0,1,1]
	v_pk_fma_f32 v[56:57], v[60:61], v[148:149], v[56:57] op_sel_hi:[0,1,1]
	v_pk_fma_f32 v[56:57], v[62:63], v[226:227], v[56:57] op_sel_hi:[0,1,1]
	v_pk_fma_f32 v[56:57], v[64:65], v[242:243], v[56:57] op_sel_hi:[0,1,1]
	v_pk_fma_f32 v[56:57], v[66:67], v[78:79], v[56:57] op_sel_hi:[0,1,1]
	v_pk_fma_f32 v[56:57], v[30:31], v[108:109], v[56:57] op_sel_hi:[0,1,1]
	v_pk_fma_f32 v[40:41], v[28:29], v[116:117], v[56:57] op_sel_hi:[0,1,1]
	v_pk_fma_f32 v[40:41], v[26:27], v[170:171], v[40:41] op_sel_hi:[0,1,1]
	v_pk_fma_f32 v[42:43], v[58:59], v[204:205], v[208:209] op_sel_hi:[0,1,1]
	v_pk_fma_f32 v[42:43], v[60:61], v[220:221], v[42:43] op_sel_hi:[0,1,1]
	v_pk_fma_f32 v[42:43], v[62:63], v[236:237], v[42:43] op_sel_hi:[0,1,1]
	v_pk_fma_f32 v[42:43], v[64:65], v[72:73], v[42:43] op_sel_hi:[0,1,1]
	v_pk_fma_f32 v[42:43], v[66:67], v[68:69], v[42:43] op_sel_hi:[0,1,1]
	v_pk_fma_f32 v[42:43], v[30:31], v[96:97], v[42:43] op_sel_hi:[0,1,1]
	v_pk_fma_f32 v[42:43], v[28:29], v[110:111], v[42:43] op_sel_hi:[0,1,1]
	v_pk_fma_f32 v[42:43], v[26:27], v[118:119], v[42:43] op_sel_hi:[0,1,1]
	v_pk_fma_f32 v[42:43], v[22:23], v[126:127], v[42:43] op_sel_hi:[0,1,1]
	v_pk_fma_f32 v[44:45], v[58:59], v[206:207], v[210:211] op_sel_hi:[0,1,1]
	v_pk_fma_f32 v[44:45], v[60:61], v[222:223], v[44:45] op_sel_hi:[0,1,1]
	v_pk_fma_f32 v[44:45], v[62:63], v[238:239], v[44:45] op_sel_hi:[0,1,1]
	v_pk_fma_f32 v[44:45], v[64:65], v[74:75], v[44:45] op_sel_hi:[0,1,1]
	v_pk_fma_f32 v[44:45], v[66:67], v[70:71], v[44:45] op_sel_hi:[0,1,1]
	v_pk_fma_f32 v[44:45], v[30:31], v[98:99], v[44:45] op_sel_hi:[0,1,1]
	v_pk_fma_f32 v[30:31], v[30:31], v[106:107], v[54:55] op_sel_hi:[0,1,1]
	v_pk_fma_f32 v[44:45], v[28:29], v[112:113], v[44:45] op_sel_hi:[0,1,1]
	v_pk_fma_f32 v[38:39], v[28:29], v[114:115], v[30:31] op_sel_hi:[0,1,1]
	v_pk_fma_f32 v[30:31], v[26:27], v[120:121], v[44:45] op_sel_hi:[0,1,1]
	v_pk_fma_f32 v[30:31], v[22:23], v[128:129], v[30:31] op_sel_hi:[0,1,1]
	v_pk_fma_f32 v[30:31], v[20:21], v[136:137], v[30:31] op_sel_hi:[0,1,1]
	v_pk_fma_f32 v[38:39], v[26:27], v[168:169], v[38:39] op_sel_hi:[0,1,1]
	v_pk_fma_f32 v[38:39], v[22:23], v[130:131], v[38:39] op_sel_hi:[0,1,1]
	v_pk_fma_f32 v[34:35], v[20:21], v[138:139], v[38:39] op_sel_hi:[0,1,1]
	v_pk_fma_f32 v[22:23], v[22:23], v[132:133], v[40:41] op_sel_hi:[0,1,1]
	v_pk_fma_f32 v[40:41], v[20:21], v[134:135], v[42:43] op_sel_hi:[0,1,1]
	v_pk_fma_f32 v[36:37], v[20:21], v[140:141], v[22:23] op_sel_hi:[0,1,1]
	v_pk_fma_f32 v[38:39], v[18:19], v[142:143], v[40:41] op_sel_hi:[0,1,1]
	v_pk_fma_f32 v[22:23], v[18:19], v[144:145], v[30:31] op_sel_hi:[0,1,1]
	v_pk_fma_f32 v[30:31], v[18:19], v[90:91], v[34:35] op_sel_hi:[0,1,1]
	v_pk_fma_f32 v[34:35], v[18:19], v[92:93], v[36:37] op_sel_hi:[0,1,1]
	global_load_dwordx4 v[18:21], v[248:249], off offset:3088
	s_movk_i32 s0, 0x104
	v_lshl_add_u32 v33, v86, 2, 0
	v_mul_lo_u32 v13, v12, s0
	v_add3_u32 v13, 0, v13, v48
	s_movk_i32 s0, 0x820
	v_and_b32_e32 v16, 0xffff0000, v233
	v_lshlrev_b32_e32 v14, 16, v234
	v_and_b32_e32 v8, 0xffff0000, v234
	v_lshlrev_b32_e32 v4, 16, v235
	v_and_b32_e32 v6, 0xffff0000, v235
	v_lshl_add_u64 v[58:59], v[24:25], 0, s[98:99]
	v_lshl_add_u64 v[44:45], v[58:59], 0, s[98:99]
	v_lshl_add_u64 v[24:25], v[44:45], 0, s[98:99]
	v_pk_fma_f32 v[36:37], v[16:17], v[158:159], v[22:23] op_sel_hi:[0,1,1]
	v_pk_fma_f32 v[38:39], v[16:17], v[156:157], v[38:39] op_sel_hi:[0,1,1]
	v_pk_fma_f32 v[28:29], v[16:17], v[162:163], v[34:35] op_sel_hi:[0,1,1]
	v_pk_fma_f32 v[26:27], v[16:17], v[160:161], v[30:31] op_sel_hi:[0,1,1]
	v_pk_fma_f32 v[30:31], v[14:15], v[164:165], v[38:39] op_sel_hi:[0,1,1]
	v_pk_fma_f32 v[34:35], v[14:15], v[166:167], v[36:37] op_sel_hi:[0,1,1]
	v_pk_fma_f32 v[26:27], v[14:15], v[122:123], v[26:27] op_sel_hi:[0,1,1]
	v_pk_fma_f32 v[22:23], v[14:15], v[124:125], v[28:29] op_sel_hi:[0,1,1]
	v_pk_fma_f32 v[28:29], v[8:9], v[174:175], v[34:35] op_sel_hi:[0,1,1]
	v_pk_fma_f32 v[30:31], v[8:9], v[172:173], v[30:31] op_sel_hi:[0,1,1]
	v_pk_fma_f32 v[22:23], v[8:9], v[178:179], v[22:23] op_sel_hi:[0,1,1]
	v_pk_fma_f32 v[8:9], v[8:9], v[176:177], v[26:27] op_sel_hi:[0,1,1]
	v_pk_fma_f32 v[26:27], v[4:5], v[180:181], v[30:31] op_sel_hi:[0,1,1]
	v_pk_fma_f32 v[28:29], v[4:5], v[182:183], v[28:29] op_sel_hi:[0,1,1]
	v_pk_fma_f32 v[30:31], v[4:5], v[196:197], v[8:9] op_sel_hi:[0,1,1]
	v_pk_fma_f32 v[4:5], v[4:5], v[198:199], v[22:23] op_sel_hi:[0,1,1]
	v_pk_fma_f32 v[14:15], v[6:7], v[216:217], v[26:27] op_sel_hi:[0,1,1]
	v_pk_fma_f32 v[8:9], v[6:7], v[218:219], v[28:29] op_sel_hi:[0,1,1]
	v_min_f32_e32 v16, 0, v14
	v_mul_f32_e64 v14, |v14|, s93
	v_exp_f32_e32 v14, v14
	s_waitcnt vmcnt(0)
; DI void gla_stage1(const Ctx& c0, int layer, int unit, LAS unsigned char* lds) {
;     ...
;         for (int j = 0; j < 8; ++j) { const float x = j < 4 ? a0[j & 3] : a1[j & 3];
;             const float ls = fminf(x, 0.f) - __logf(1.f + __expf(-fabsf(x)));
;             LA[cc * 65 + 8 * ch + j] = ls * (1.f / 16.f); }
;     }
;     __syncthreads();
;     {
;         const int d = tid & 63, part = tid >> 6; float v[8]; float run = 0.f;
; #pragma unroll
;         for (int j = 0; j < 8; ++j) { run += LA[(8 * part + j) * 65 + d]; v[j] = run; }
;         PART[part * 64 + d] = run;
;         __syncthreads();
;         float off = 0.f;
; #pragma unroll
;         for (int p = 0; p < 8; ++p) off += (p < part) ? PART[p * 64 + d] : 0.f;
	v_pk_fma_f32 v[4:5], v[6:7], v[20:21], v[4:5] op_sel_hi:[0,1,1]
	v_pk_fma_f32 v[6:7], v[6:7], v[18:19], v[30:31] op_sel_hi:[0,1,1]
	v_mov_b32_e32 v20, 0
	v_add_f32_e32 v14, 1.0, v14
	v_cmp_gt_f32_e32 vcc, s94, v14
	v_mov_b32_e32 v21, 0
	s_nop 0
	v_cndmask_b32_e64 v17, 0, 32, vcc
	v_ldexp_f32 v14, v14, v17
	v_log_f32_e32 v14, v14
	s_nop 0
	v_mul_f32_e32 v17, 0x3f317217, v14
	v_fma_f32 v17, v14, s95, -v17
	v_fmac_f32_e32 v17, 0x3377d1cf, v14
	v_fmac_f32_e32 v17, 0x3f317217, v14
	v_cmp_lt_f32_e64 s[72:73], |v14|, s96
	s_nop 1
	v_cndmask_b32_e64 v14, v14, v17, s[72:73]
	v_cndmask_b32_e32 v17, 0, v47, vcc
	v_sub_f32_e32 v14, v14, v17
	v_min_f32_e32 v17, 0, v15
	v_mul_f32_e64 v15, |v15|, s93
	v_exp_f32_e32 v15, v15
	s_nop 0
	v_add_f32_e32 v15, 1.0, v15
	v_cmp_gt_f32_e32 vcc, s94, v15
	s_nop 1
	v_cndmask_b32_e64 v18, 0, 32, vcc
	v_ldexp_f32 v15, v15, v18
	v_log_f32_e32 v15, v15
	s_nop 0
	v_mul_f32_e32 v18, 0x3f317217, v15
	v_fma_f32 v18, v15, s95, -v18
	v_fmac_f32_e32 v18, 0x3377d1cf, v15
	v_fmac_f32_e32 v18, 0x3f317217, v15
	v_cmp_lt_f32_e64 s[72:73], |v15|, s96
	s_nop 1
	v_cndmask_b32_e64 v15, v15, v18, s[72:73]
	v_cndmask_b32_e32 v18, 0, v47, vcc
	v_sub_f32_e32 v15, v15, v18
	v_pk_add_f32 v[14:15], v[16:17], v[14:15] neg_lo:[0,1] neg_hi:[0,1]
	v_ashrrev_i32_e32 v17, 6, v86
	v_pk_mul_f32 v[14:15], v[14:15], s[8:9] op_sel_hi:[1,0]
	ds_write2_b32 v13, v14, v15 offset1:1
	v_min_f32_e32 v14, 0, v8
	v_mul_f32_e64 v8, |v8|, s93
	v_exp_f32_e32 v8, v8
	s_nop 0
	v_add_f32_e32 v8, 1.0, v8
	v_cmp_gt_f32_e32 vcc, s94, v8
	s_nop 1
	v_cndmask_b32_e64 v15, 0, 32, vcc
	v_ldexp_f32 v8, v8, v15
	v_log_f32_e32 v8, v8
	s_nop 0
	v_mul_f32_e32 v15, 0x3f317217, v8
	v_fma_f32 v15, v8, s95, -v15
	v_fmac_f32_e32 v15, 0x3377d1cf, v8
	v_fmac_f32_e32 v15, 0x3f317217, v8
	v_cmp_lt_f32_e64 s[72:73], |v8|, s96
	s_nop 1
	v_cndmask_b32_e64 v8, v8, v15, s[72:73]
	v_cndmask_b32_e32 v15, 0, v47, vcc
	v_sub_f32_e32 v8, v8, v15
	v_min_f32_e32 v15, 0, v9
	v_mul_f32_e64 v9, |v9|, s93
	v_exp_f32_e32 v9, v9
	s_nop 0
	v_add_f32_e32 v9, 1.0, v9
	v_cmp_gt_f32_e32 vcc, s94, v9
	s_nop 1
	v_cndmask_b32_e64 v16, 0, 32, vcc
	v_ldexp_f32 v9, v9, v16
	v_log_f32_e32 v9, v9
	s_nop 0
	v_mul_f32_e32 v16, 0x3f317217, v9
	v_fma_f32 v16, v9, s95, -v16
	v_fmac_f32_e32 v16, 0x3377d1cf, v9
	v_fmac_f32_e32 v16, 0x3f317217, v9
	v_cmp_lt_f32_e64 s[72:73], |v9|, s96
	s_nop 1
	v_cndmask_b32_e64 v9, v9, v16, s[72:73]
	v_cndmask_b32_e32 v16, 0, v47, vcc
	v_sub_f32_e32 v9, v9, v16
	v_pk_add_f32 v[8:9], v[14:15], v[8:9] neg_lo:[0,1] neg_hi:[0,1]
	v_pk_mul_f32 v[8:9], v[8:9], s[8:9] op_sel_hi:[1,0]
	ds_write2_b32 v13, v8, v9 offset0:2 offset1:3
	v_min_f32_e32 v8, 0, v6
	v_mul_f32_e64 v6, |v6|, s93
	v_exp_f32_e32 v6, v6
	s_nop 0
	v_add_f32_e32 v6, 1.0, v6
	v_cmp_gt_f32_e32 vcc, s94, v6
	s_nop 1
	v_cndmask_b32_e64 v9, 0, 32, vcc
	v_ldexp_f32 v6, v6, v9
	v_log_f32_e32 v6, v6
	s_nop 0
	v_mul_f32_e32 v9, 0x3f317217, v6
	v_fma_f32 v9, v6, s95, -v9
	v_fmac_f32_e32 v9, 0x3377d1cf, v6
	v_fmac_f32_e32 v9, 0x3f317217, v6
	v_cmp_lt_f32_e64 s[72:73], |v6|, s96
	s_nop 1
	v_cndmask_b32_e64 v6, v6, v9, s[72:73]
	v_cndmask_b32_e32 v9, 0, v47, vcc
	v_sub_f32_e32 v6, v6, v9
	v_min_f32_e32 v9, 0, v7
	v_mul_f32_e64 v7, |v7|, s93
	v_exp_f32_e32 v7, v7
	s_nop 0
	v_add_f32_e32 v7, 1.0, v7
	v_cmp_gt_f32_e32 vcc, s94, v7
	s_nop 1
	v_cndmask_b32_e64 v14, 0, 32, vcc
	v_ldexp_f32 v7, v7, v14
	v_log_f32_e32 v7, v7
	s_nop 0
	v_mul_f32_e32 v14, 0x3f317217, v7
	v_fma_f32 v14, v7, s95, -v14
	v_fmac_f32_e32 v14, 0x3377d1cf, v7
	v_fmac_f32_e32 v14, 0x3f317217, v7
	v_cmp_lt_f32_e64 s[72:73], |v7|, s96
	s_nop 1
	v_cndmask_b32_e64 v7, v7, v14, s[72:73]
	v_cndmask_b32_e32 v14, 0, v47, vcc
	v_sub_f32_e32 v7, v7, v14
	v_pk_add_f32 v[6:7], v[8:9], v[6:7] neg_lo:[0,1] neg_hi:[0,1]
	v_pk_mul_f32 v[6:7], v[6:7], s[8:9] op_sel_hi:[1,0]
	ds_write2_b32 v13, v6, v7 offset0:4 offset1:5
	v_min_f32_e32 v6, 0, v4
	v_mul_f32_e64 v4, |v4|, s93
	v_exp_f32_e32 v4, v4
	s_nop 0
	v_add_f32_e32 v4, 1.0, v4
	v_cmp_gt_f32_e32 vcc, s94, v4
	s_nop 1
	v_cndmask_b32_e64 v7, 0, 32, vcc
	v_ldexp_f32 v4, v4, v7
	v_log_f32_e32 v4, v4
	s_nop 0
	v_mul_f32_e32 v7, 0x3f317217, v4
	v_fma_f32 v7, v4, s95, -v7
	v_fmac_f32_e32 v7, 0x3377d1cf, v4
	v_fmac_f32_e32 v7, 0x3f317217, v4
	v_cmp_lt_f32_e64 s[72:73], |v4|, s96
	s_nop 1
	v_cndmask_b32_e64 v4, v4, v7, s[72:73]
	v_cndmask_b32_e32 v7, 0, v47, vcc
	v_sub_f32_e32 v4, v4, v7
	v_min_f32_e32 v7, 0, v5
	v_mul_f32_e64 v5, |v5|, s93
	v_exp_f32_e32 v5, v5
	s_nop 0
	v_add_f32_e32 v5, 1.0, v5
	v_cmp_gt_f32_e32 vcc, s94, v5
	s_nop 1
	v_cndmask_b32_e64 v8, 0, 32, vcc
	v_ldexp_f32 v5, v5, v8
	v_log_f32_e32 v5, v5
	s_nop 0
	v_mul_f32_e32 v8, 0x3f317217, v5
	v_fma_f32 v8, v5, s95, -v8
	v_fmac_f32_e32 v8, 0x3377d1cf, v5
	v_fmac_f32_e32 v8, 0x3f317217, v5
	v_cmp_lt_f32_e64 s[72:73], |v5|, s96
	s_nop 1
	v_cndmask_b32_e64 v5, v5, v8, s[72:73]
	v_cndmask_b32_e32 v8, 0, v47, vcc
	v_sub_f32_e32 v5, v5, v8
	v_pk_add_f32 v[4:5], v[6:7], v[4:5] neg_lo:[0,1] neg_hi:[0,1]
	v_cmp_lt_i32_e32 vcc, 0, v17
	v_pk_mul_f32 v[4:5], v[4:5], s[8:9] op_sel_hi:[1,0]
	ds_write2_b32 v13, v4, v5 offset0:6 offset1:7
	v_and_b32_e32 v4, 63, v86
	v_lshl_add_u32 v14, v4, 2, 0
	v_mul_lo_u32 v4, v17, s0
	v_add_u32_e32 v4, v14, v4
	v_mov_b32_e32 v10, v86
	v_mov_b32_e32 v80, v94
	v_mov_b32_e32 v32, v102
	s_waitcnt vmcnt(0) lgkmcnt(0)
.Lg1j_l0:
	s_barrier
	ds_read2_b32 v[6:7], v4 offset1:65
	ds_read2_b32 v[8:9], v4 offset0:130 offset1:195
	s_waitcnt lgkmcnt(1)
	v_add_f32_e32 v5, 0, v6
	v_add_f32_e32 v6, v5, v7
	s_waitcnt lgkmcnt(0)
	v_add_f32_e32 v7, v6, v8
	v_add_f32_e32 v8, v7, v9
	v_add_u32_e32 v9, 0x400, v4
	ds_read2_b32 v[18:19], v9 offset0:4 offset1:69
	s_waitcnt lgkmcnt(0)
	v_add_f32_e32 v15, v8, v18
	v_add_f32_e32 v16, v15, v19
	ds_read2_b32 v[18:19], v9 offset0:134 offset1:199
	s_waitcnt lgkmcnt(0)
	v_add_f32_e32 v18, v16, v18
	v_add_f32_e32 v19, v18, v19
	ds_write_b32 v33, v19 offset:16640
	s_waitcnt lgkmcnt(0)
	s_barrier
	s_and_saveexec_b64 s[72:73], vcc
	s_cbranch_execz .LBB0_402
	ds_read_b32 v21, v14 offset:16640
	s_waitcnt lgkmcnt(0)
	v_add_f32_e32 v21, 0, v21

; #define LAS __attribute__((address_space(3)))
; DI int crow(int reg, int hi) { return (reg & 3) + 8 * (reg >> 2) + 4 * hi; }
; #define MFMA32(a, b, c) __builtin_amdgcn_mfma_f32_32x32x16_bf16((a), (b), (c), 0, 0, 0)
; DI void gla_stage1(const Ctx& c0, int layer, int unit, LAS unsigned char* lds) {
;     ...
;     const int bh = unit >> 6, n = unit & 63, b = bh >> 2, h = bh & 3;
;     const size_t row0 = (size_t)b * SEQ + n * 64;
;     LAS float* LA = (LAS float*)(lds + G1_LA); LAS float* PART = (LAS float*)(lds + G1_PART);
;     const bf16* gq = (const bf16*)(c.ws + O_GQ); const bf16* gk = (const bf16*)(c.ws + O_GK); const bf16* gv = (const bf16*)(c.ws + O_GV);
;     const bf16* misc = (const bf16*)(c.ws + O_MISC);
;     const float* Wa = c.a->in[I_GWA] + (size_t)layer * 16 * 256 + h * 64; const float* ba = c.a->in[I_GBA] + (size_t)layer * 256 + h * 64;
;     const int cc = tid >> 3, ch = tid & 7;
;     ...
;             if (jb <= cb) {
; #pragma unroll
;                 for (int s = 0; s < 4; ++s) { const bf16x8 a = *(const LAS bf16x8*)(kb + s * 2048 + jb * 512); x = MFMA32(a, qf[s], x); }
; #pragma unroll
;                 for (int rg = 0; rg < 16; ++rg) { const int j = 32 * jb + crow(rg, hi); if (j > cl) x[rg] = 0.f; }
.LBB0_1006:
	v_writelane_b32 v250, s72, 20
	s_cmp_lt_i32 s7, 1
	s_nop 0
	v_writelane_b32 v250, s73, 21
	v_writelane_b32 v250, s74, 22
	s_nop 1
	v_writelane_b32 v250, s75, 23
	v_writelane_b32 v250, s88, 8
	s_nop 1
	v_writelane_b32 v250, s89, 9
	s_cbranch_scc1 .LBB0_1037
	s_lshl_b32 s0, s78, 1
	s_load_dwordx4 s[76:79], s[90:91], 0x48
	v_lshlrev_b32_e32 v2, 2, v153
	v_or_b32_e32 v6, 32, v2
	v_lshlrev_b32_e32 v3, 4, v152
	s_mov_b32 s1, 0
	s_waitcnt lgkmcnt(0)
	s_add_u32 s33, s76, 0x4000
	s_addc_u32 s77, s77, 0
	s_bfe_u32 s4, s82, 0x10006
	s_lshl_b32 s5, s4, 5
	v_or_b32_e32 v1, s5, v152
	v_cmp_gt_u32_e64 s[8:9], v6, v1
	v_cmp_lt_u32_e64 s[10:11], v6, v1
	v_or_b32_e32 v6, 34, v2
	v_cmp_gt_u32_e64 s[12:13], v6, v1
	v_or_b32_e32 v6, 35, v2
	v_cmp_gt_u32_e64 s[14:15], v6, v1
	v_or_b32_e32 v6, 40, v2
	v_cmp_gt_u32_e64 s[16:17], v6, v1
	v_or_b32_e32 v6, 41, v2
	v_cmp_gt_u32_e64 s[18:19], v6, v1
	v_or_b32_e32 v6, 42, v2
	v_cmp_gt_u32_e64 s[20:21], v6, v1
	v_or_b32_e32 v6, 43, v2
	v_cmp_gt_u32_e64 s[22:23], v6, v1
	v_or_b32_e32 v6, 48, v2
	v_cmp_gt_u32_e64 s[24:25], v6, v1
	v_or_b32_e32 v6, 49, v2
	v_cmp_gt_u32_e64 s[26:27], v6, v1
	v_or_b32_e32 v6, 50, v2
	v_cmp_gt_u32_e64 s[28:29], v6, v1
	v_or_b32_e32 v6, 51, v2
	v_cmp_gt_u32_e64 s[30:31], v6, v1
	v_or_b32_e32 v6, 56, v2
	v_cmp_gt_u32_e64 s[34:35], v6, v1
	v_or_b32_e32 v6, 57, v2
	v_cmp_gt_u32_e64 s[36:37], v6, v1
	v_or_b32_e32 v6, 58, v2
	v_cmp_gt_u32_e64 s[38:39], v6, v1
	v_or_b32_e32 v6, 59, v2
	v_cmp_gt_u32_e64 s[40:41], v6, v1
	v_or_b32_e32 v6, 27, v2
	v_cmp_gt_u32_e64 s[42:43], v6, v1
	v_or_b32_e32 v6, 26, v2
	v_cmp_gt_u32_e64 s[44:45], v6, v1
	v_or_b32_e32 v6, 25, v2
	v_cmp_gt_u32_e64 s[46:47], v6, v1
	v_or_b32_e32 v6, 24, v2
	v_cmp_gt_u32_e64 s[48:49], v6, v1
	v_or_b32_e32 v6, 19, v2
	v_cmp_gt_u32_e64 s[50:51], v6, v1
	v_or_b32_e32 v6, 18, v2
	v_cmp_gt_u32_e64 s[52:53], v6, v1
	v_or_b32_e32 v6, 17, v2
	v_cmp_gt_u32_e64 s[54:55], v6, v1
	v_or_b32_e32 v6, 16, v2
	v_cmp_gt_u32_e64 s[56:57], v6, v1
	v_or_b32_e32 v6, 11, v2
	v_cmp_gt_u32_e64 s[58:59], v6, v1
	v_or_b32_e32 v6, 10, v2
	v_cmp_gt_u32_e64 s[60:61], v6, v1
	v_or_b32_e32 v6, 9, v2
	v_cmp_gt_u32_e64 s[62:63], v6, v1
	v_or_b32_e32 v6, 8, v2
	v_writelane_b32 v250, s8, 27
	v_cmp_gt_u32_e64 s[64:65], v6, v1
	v_or_b32_e32 v6, 3, v2
	s_bitcmp1_b32 s82, 6
	v_writelane_b32 v250, s9, 28
	v_cmp_gt_u32_e64 s[66:67], v6, v1
	v_or_b32_e32 v6, 2, v2
	v_lshlrev_b32_e32 v5, 4, v1
	s_cselect_b64 s[2:3], -1, 0
	v_cmp_gt_u32_e64 s[68:69], v6, v1
	v_cmp_lt_u32_e64 s[70:71], v2, v1
	v_cmp_gt_u32_e64 s[72:73], v2, v1
	v_and_or_b32 v1, v188, 3, v2
	v_readlane_b32 s8, v250, 32
	s_lshl_b32 s4, s4, 12
	v_or_b32_e32 v46, s5, v2
	v_lshl_add_u32 v4, v153, 10, 0
	v_lshlrev_b32_e32 v1, 6, v1
	v_and_b32_e32 v6, 32, v187
	v_and_b32_e32 v7, 24, v186
	s_lshl_b32 s6, s8, 12
	s_add_i32 s91, s4, 0
	s_lshl_b32 s4, s8, 5
	v_lshlrev_b32_e32 v2, 7, v46
	v_or3_b32 v1, v1, v6, v7
	s_add_i32 s90, s6, 0
	v_mov_b32_e32 v49, 0
	s_mov_b32 s5, s1
	s_addk_i32 s0, 0x5f9
	s_movk_i32 s93, 0x3000
	s_movk_i32 s94, 0x1000
	s_movk_i32 s95, 0x2000
	s_mov_b32 s96, 0xbfb8aa3b
	s_mov_b32 s97, 0x800000
	s_mov_b32 s92, 0x3f317217
	s_mov_b32 s8, 0x7f800000
	v_mov_b32_e32 v47, 0x41b17218
	s_mov_b32 s6, 0x3d800000
	s_mov_b32 s76, 0x3e000000
	v_add_u32_e32 v52, v4, v5
	s_lshl_b32 s80, s4, 1
	v_lshlrev_b32_e32 v50, 2, v2
	v_add_u32_e32 v53, v4, v3
	s_mov_b32 s9, 0
	v_writelane_b32 v250, s0, 33
	s_mov_b32 s101, -1
	s_branch .LBB0_1009

; #define LAS __attribute__((address_space(3)))
; DI float bflo(unsigned w) { return __uint_as_float(w << 16); }
; DI float bfhi(unsigned w) { return __uint_as_float(w & 0xffff0000u); }
; DI void gla_stage1(const Ctx& c0, int layer, int unit, LAS unsigned char* lds) {
;     ...
;     const int cc = tid >> 3, ch = tid & 7;
; #pragma unroll
;     for (int it = 0; it < 2; ++it) { const int idx = tid + 512 * it, vc_ = idx & 15, c_ = idx >> 4;
;         const u32x4 v = *(const u32x4*)(gv + (row0 + c_) * 512 + h * 128 + vc_ * 8);
;         *(LAS u32x4*)(lds + G1_VI + (vc_ >> 2) * 4096 + c_ * 64 + (vc_ & 3) * 16) = v; }
;     {
;         float ga[16];
;         { const u32x4 g0 = *(const u32x4*)(misc + (row0 + cc) * 64 + 32), g1 = *(const u32x4*)(misc + (row0 + cc) * 64 + 40);
;           ga[0] = bflo(g0.x); ga[1] = bfhi(g0.x); ga[2] = bflo(g0.y); ga[3] = bfhi(g0.y); ga[4] = bflo(g0.z); ga[5] = bfhi(g0.z); ga[6] = bflo(g0.w); ga[7] = bfhi(g0.w);
;           ga[8] = bflo(g1.x); ga[9] = bfhi(g1.x); ga[10] = bflo(g1.y); ga[11] = bfhi(g1.y); ga[12] = bflo(g1.z); ga[13] = bfhi(g1.z); ga[14] = bflo(g1.w); ga[15] = bfhi(g1.w); }
;         f32x4 a0 = *(const f32x4*)(ba + 8 * ch), a1 = *(const f32x4*)(ba + 8 * ch + 4);
;         const float* wap = Wa + 8 * ch; asm volatile("" : "+v"(wap));
; #pragma unroll
;         for (int rr = 0; rr < 16; ++rr) { const f32x4 w0 = *(const f32x4*)(wap + rr * 256), w1 = *(const f32x4*)(wap + rr * 256 + 4); a0 += w0 * ga[rr]; a1 += w1 * ga[rr]; }
.LBB0_1016:
	s_bfe_u32 s100, s82, 0x20006
	s_cmp_eq_u32 s100, s101
	s_mov_b32 s101, s100
	s_cbranch_scc1 .Lg1b_l1
	s_mov_b64 s[98:99], 0x1000
	s_mov_b64 vcc, 0x1b500000
	v_mov_b32_e32 v82, v151
	v_add_u32_e32 v94, 0x200, v82
	v_ashrrev_i32_e32 v78, 4, v94
	v_ashrrev_i32_e32 v79, 31, v78
	v_and_b32_e32 v102, 7, v82
	s_mov_b64 s[74:75], s[84:85]
	s_mov_b64 s[84:85], s[86:87]
	s_ashr_i32 s74, s82, 8
	s_ashr_i32 s75, s74, 31
	v_and_b32_e32 v88, 15, v82
	v_lshlrev_b32_e32 v48, 4, v88
	v_lshlrev_b32_e32 v3, 4, v82
	v_ashrrev_i32_e32 v8, 4, v82
	v_ashrrev_i32_e32 v9, 31, v8
	v_and_b32_e32 v11, 48, v3
	s_lshl_b32 s0, s82, 6
	s_bfe_u32 s81, s82, 0x20006
	s_lshl_b64 s[86:87], s[74:75], 12
	s_and_b32 s0, s0, 0xfc0
	s_or_b32 s86, s86, s0
	v_lshl_add_u64 v[76:77], s[86:87], 0, v[78:79]
	v_lshlrev_b64 v[74:75], 10, v[76:77]
	s_lshl_b32 s0, s81, 8
	s_add_u32 s74, s84, s0
	s_addc_u32 s75, s85, 0
	v_lshl_add_u64 v[100:101], s[74:75], 0, v[48:49]
	v_lshlrev_b32_e32 v48, 5, v102
	s_mov_b64 s[74:75], 0xf500000
	v_lshl_add_u64 v[6:7], v[100:101], 0, s[74:75]
	v_lshl_add_u64 v[80:81], v[6:7], 0, v[74:75]
	global_load_dwordx4 v[228:231], v[80:81], off
	s_add_u32 s74, s33, s0
	s_addc_u32 s75, s77, 0
	v_lshl_add_u64 v[24:25], s[74:75], 0, v[48:49]
	global_load_dwordx4 v[196:199], v[24:25], off offset:16
	global_load_dwordx4 v[200:203], v[24:25], off
	global_load_dwordx4 v[142:145], v[24:25], off offset:1040
	global_load_dwordx4 v[216:219], v[24:25], off offset:1024
	global_load_dwordx4 v[220:223], v[24:25], off offset:2064
	global_load_dwordx4 v[236:239], v[24:25], off offset:2048
	global_load_dwordx4 v[240:243], v[24:25], off offset:3088
	global_load_dwordx4 v[72:75], v[24:25], off offset:3072
	s_add_u32 s88, s78, s0
	s_addc_u32 s89, s79, 0
	global_load_dwordx4 v[204:207], v48, s[88:89] offset:1024
	global_load_dwordx4 v[208:211], v48, s[88:89] offset:1040
	v_lshl_add_u64 v[244:245], v[24:25], 0, s[98:99]
	global_load_dwordx4 v[164:167], v[244:245], off offset:3088
	global_load_dwordx4 v[114:117], v[244:245], off offset:3072
	global_load_dwordx4 v[110:113], v[244:245], off offset:2064
	global_load_dwordx4 v[106:109], v[244:245], off offset:2048
	global_load_dwordx4 v[96:99], v[244:245], off offset:1040
	global_load_dwordx4 v[90:93], v[244:245], off offset:1024
	global_load_dwordx4 v[68:71], v[244:245], off
	v_lshl_add_u64 v[246:247], v[244:245], 0, s[98:99]
	global_load_dwordx4 v[84:87], v[246:247], off offset:2064
	global_load_dwordx4 v[138:141], v[246:247], off offset:2048
	global_load_dwordx4 v[134:137], v[246:247], off offset:1040
	global_load_dwordx4 v[130:133], v[246:247], off offset:1024
	global_load_dwordx4 v[126:129], v[246:247], off offset:16
	global_load_dwordx4 v[122:125], v[246:247], off
	global_load_dwordx4 v[156:159], v[246:247], off offset:3088
	global_load_dwordx4 v[146:149], v[246:247], off offset:3072
	v_lshl_add_u64 v[248:249], v[246:247], 0, s[98:99]
	global_load_dwordx4 v[212:215], v[248:249], off offset:3072
	global_load_dwordx4 v[180:183], v[248:249], off offset:2064
	global_load_dwordx4 v[176:179], v[248:249], off offset:2048
	global_load_dwordx4 v[172:175], v[248:249], off offset:1040
	global_load_dwordx4 v[168:171], v[248:249], off offset:1024
	global_load_dwordx4 v[118:121], v[248:249], off offset:16
	global_load_dwordx4 v[160:163], v[248:249], off
	v_lshlrev_b32_e32 v2, 10, v82
	v_and_b32_e32 v2, 0x3000, v2
	v_add3_u32 v13, 0, v2, v11
	v_lshl_add_u64 v[2:3], s[86:87], 0, v[8:9]
	v_lshlrev_b64 v[2:3], 10, v[2:3]
	v_lshl_add_u64 v[2:3], v[6:7], 0, v[2:3]
	global_load_dwordx4 v[224:227], v[2:3], off
	v_lshl_add_u32 v6, v78, 6, v13
	global_load_dwordx4 v[76:79], v[244:245], off offset:16
	v_lshl_add_u32 v8, v8, 6, v13
	s_waitcnt vmcnt(1)
	ds_write_b128 v8, v[224:227] offset:43264
	ds_write_b128 v6, v[228:231] offset:43264
	v_ashrrev_i32_e32 v12, 3, v82
	v_ashrrev_i32_e32 v13, 31, v12
	v_lshl_add_u64 v[2:3], s[86:87], 0, v[12:13]
	v_lshlrev_b64 v[4:5], 7, v[2:3]
	v_lshl_add_u64 v[4:5], s[84:85], 0, v[4:5]
	v_lshl_add_u64 v[8:9], v[4:5], 0, vcc
	global_load_dwordx4 v[4:7], v[8:9], off offset:64
	global_load_dwordx4 v[232:235], v[8:9], off offset:80
	s_waitcnt vmcnt(0)
	v_and_b32_e32 v20, 0xffff0000, v232
	v_lshlrev_b32_e32 v18, 16, v233
	v_lshlrev_b32_e32 v22, 16, v232
	v_and_b32_e32 v26, 0xffff0000, v7
	v_lshlrev_b32_e32 v28, 16, v7
	v_and_b32_e32 v30, 0xffff0000, v6
	v_lshlrev_b32_e32 v66, 16, v6
	v_and_b32_e32 v64, 0xffff0000, v5
	v_lshlrev_b32_e32 v62, 16, v5
	v_and_b32_e32 v60, 0xffff0000, v4
	v_lshlrev_b32_e32 v58, 16, v4
	v_pk_fma_f32 v[54:55], v[58:59], v[196:197], v[208:209] op_sel_hi:[0,1,1]
	v_pk_fma_f32 v[54:55], v[60:61], v[142:143], v[54:55] op_sel_hi:[0,1,1]
	v_pk_fma_f32 v[54:55], v[62:63], v[220:221], v[54:55] op_sel_hi:[0,1,1]
	v_pk_fma_f32 v[54:55], v[64:65], v[240:241], v[54:55] op_sel_hi:[0,1,1]
	v_pk_fma_f32 v[54:55], v[66:67], v[76:77], v[54:55] op_sel_hi:[0,1,1]
	v_pk_fma_f32 v[56:57], v[58:59], v[198:199], v[210:211] op_sel_hi:[0,1,1]
	v_pk_fma_f32 v[56:57], v[60:61], v[144:145], v[56:57] op_sel_hi:[0,1,1]
	v_pk_fma_f32 v[56:57], v[62:63], v[222:223], v[56:57] op_sel_hi:[0,1,1]
	v_pk_fma_f32 v[56:57], v[64:65], v[242:243], v[56:57] op_sel_hi:[0,1,1]
	v_pk_fma_f32 v[56:57], v[66:67], v[78:79], v[56:57] op_sel_hi:[0,1,1]
	v_pk_fma_f32 v[56:57], v[30:31], v[98:99], v[56:57] op_sel_hi:[0,1,1]
	v_pk_fma_f32 v[40:41], v[28:29], v[112:113], v[56:57] op_sel_hi:[0,1,1]
	v_pk_fma_f32 v[40:41], v[26:27], v[166:167], v[40:41] op_sel_hi:[0,1,1]
	v_pk_fma_f32 v[42:43], v[58:59], v[200:201], v[204:205] op_sel_hi:[0,1,1]
	v_pk_fma_f32 v[42:43], v[60:61], v[216:217], v[42:43] op_sel_hi:[0,1,1]
; DI float bflo(unsigned w) { return __uint_as_float(w << 16); }
; DI float bfhi(unsigned w) { return __uint_as_float(w & 0xffff0000u); }
; DI void gla_stage1(const Ctx& c0, int layer, int unit, LAS unsigned char* lds) {
;     ...
;         { const u32x4 g0 = *(const u32x4*)(misc + (row0 + cc) * 64 + 32), g1 = *(const u32x4*)(misc + (row0 + cc) * 64 + 40);
;           ga[0] = bflo(g0.x); ga[1] = bfhi(g0.x); ga[2] = bflo(g0.y); ga[3] = bfhi(g0.y); ga[4] = bflo(g0.z); ga[5] = bfhi(g0.z); ga[6] = bflo(g0.w); ga[7] = bfhi(g0.w);
;           ga[8] = bflo(g1.x); ga[9] = bfhi(g1.x); ga[10] = bflo(g1.y); ga[11] = bfhi(g1.y); ga[12] = bflo(g1.z); ga[13] = bfhi(g1.z); ga[14] = bflo(g1.w); ga[15] = bfhi(g1.w); }
;         f32x4 a0 = *(const f32x4*)(ba + 8 * ch), a1 = *(const f32x4*)(ba + 8 * ch + 4);
;         const float* wap = Wa + 8 * ch; asm volatile("" : "+v"(wap));
; #pragma unroll
;         for (int rr = 0; rr < 16; ++rr) { const f32x4 w0 = *(const f32x4*)(wap + rr * 256), w1 = *(const f32x4*)(wap + rr * 256 + 4); a0 += w0 * ga[rr]; a1 += w1 * ga[rr]; }
; #pragma unroll
;         for (int j = 0; j < 8; ++j) { const float x = j < 4 ? a0[j & 3] : a1[j & 3];
;             const float ls = fminf(x, 0.f) - __logf(1.f + __expf(-fabsf(x)));
;             LA[cc * 65 + 8 * ch + j] = ls * (1.f / 16.f); }
	v_pk_fma_f32 v[42:43], v[62:63], v[236:237], v[42:43] op_sel_hi:[0,1,1]
	v_pk_fma_f32 v[42:43], v[64:65], v[72:73], v[42:43] op_sel_hi:[0,1,1]
	v_pk_fma_f32 v[42:43], v[66:67], v[68:69], v[42:43] op_sel_hi:[0,1,1]
	v_pk_fma_f32 v[42:43], v[30:31], v[90:91], v[42:43] op_sel_hi:[0,1,1]
	v_pk_fma_f32 v[42:43], v[28:29], v[106:107], v[42:43] op_sel_hi:[0,1,1]
	v_pk_fma_f32 v[42:43], v[26:27], v[114:115], v[42:43] op_sel_hi:[0,1,1]
	v_pk_fma_f32 v[42:43], v[22:23], v[122:123], v[42:43] op_sel_hi:[0,1,1]
	v_pk_fma_f32 v[44:45], v[58:59], v[202:203], v[206:207] op_sel_hi:[0,1,1]
	v_pk_fma_f32 v[44:45], v[60:61], v[218:219], v[44:45] op_sel_hi:[0,1,1]
	v_pk_fma_f32 v[44:45], v[62:63], v[238:239], v[44:45] op_sel_hi:[0,1,1]
	v_pk_fma_f32 v[44:45], v[64:65], v[74:75], v[44:45] op_sel_hi:[0,1,1]
	v_pk_fma_f32 v[44:45], v[66:67], v[70:71], v[44:45] op_sel_hi:[0,1,1]
	v_pk_fma_f32 v[44:45], v[30:31], v[92:93], v[44:45] op_sel_hi:[0,1,1]
	v_pk_fma_f32 v[30:31], v[30:31], v[96:97], v[54:55] op_sel_hi:[0,1,1]
	v_pk_fma_f32 v[44:45], v[28:29], v[108:109], v[44:45] op_sel_hi:[0,1,1]
	v_pk_fma_f32 v[38:39], v[28:29], v[110:111], v[30:31] op_sel_hi:[0,1,1]
	v_pk_fma_f32 v[30:31], v[26:27], v[116:117], v[44:45] op_sel_hi:[0,1,1]
	v_pk_fma_f32 v[30:31], v[22:23], v[124:125], v[30:31] op_sel_hi:[0,1,1]
	v_pk_fma_f32 v[30:31], v[20:21], v[132:133], v[30:31] op_sel_hi:[0,1,1]
	v_pk_fma_f32 v[38:39], v[26:27], v[164:165], v[38:39] op_sel_hi:[0,1,1]
	v_pk_fma_f32 v[38:39], v[22:23], v[126:127], v[38:39] op_sel_hi:[0,1,1]
	v_pk_fma_f32 v[34:35], v[20:21], v[134:135], v[38:39] op_sel_hi:[0,1,1]
	v_pk_fma_f32 v[22:23], v[22:23], v[128:129], v[40:41] op_sel_hi:[0,1,1]
	v_pk_fma_f32 v[40:41], v[20:21], v[130:131], v[42:43] op_sel_hi:[0,1,1]
	v_pk_fma_f32 v[36:37], v[20:21], v[136:137], v[22:23] op_sel_hi:[0,1,1]
	v_pk_fma_f32 v[38:39], v[18:19], v[138:139], v[40:41] op_sel_hi:[0,1,1]
	v_pk_fma_f32 v[22:23], v[18:19], v[140:141], v[30:31] op_sel_hi:[0,1,1]
	v_pk_fma_f32 v[30:31], v[18:19], v[84:85], v[34:35] op_sel_hi:[0,1,1]
	v_pk_fma_f32 v[34:35], v[18:19], v[86:87], v[36:37] op_sel_hi:[0,1,1]
	global_load_dwordx4 v[18:21], v[248:249], off offset:3088
	s_movk_i32 s0, 0x104
	v_lshl_add_u32 v33, v82, 2, 0
	v_mul_lo_u32 v13, v12, s0
	v_add3_u32 v13, 0, v13, v48
	s_movk_i32 s0, 0x820
	v_and_b32_e32 v16, 0xffff0000, v233
	v_lshlrev_b32_e32 v14, 16, v234
	v_and_b32_e32 v8, 0xffff0000, v234
	v_lshlrev_b32_e32 v4, 16, v235
	v_and_b32_e32 v6, 0xffff0000, v235
	v_lshl_add_u64 v[58:59], v[24:25], 0, s[98:99]
	v_lshl_add_u64 v[44:45], v[58:59], 0, s[98:99]
	v_lshl_add_u64 v[24:25], v[44:45], 0, s[98:99]
	v_pk_fma_f32 v[36:37], v[16:17], v[148:149], v[22:23] op_sel_hi:[0,1,1]
	v_pk_fma_f32 v[38:39], v[16:17], v[146:147], v[38:39] op_sel_hi:[0,1,1]
	v_pk_fma_f32 v[28:29], v[16:17], v[158:159], v[34:35] op_sel_hi:[0,1,1]
	v_pk_fma_f32 v[26:27], v[16:17], v[156:157], v[30:31] op_sel_hi:[0,1,1]
	v_pk_fma_f32 v[30:31], v[14:15], v[160:161], v[38:39] op_sel_hi:[0,1,1]
	v_pk_fma_f32 v[34:35], v[14:15], v[162:163], v[36:37] op_sel_hi:[0,1,1]
	v_pk_fma_f32 v[26:27], v[14:15], v[118:119], v[26:27] op_sel_hi:[0,1,1]
	v_pk_fma_f32 v[22:23], v[14:15], v[120:121], v[28:29] op_sel_hi:[0,1,1]
	v_pk_fma_f32 v[28:29], v[8:9], v[170:171], v[34:35] op_sel_hi:[0,1,1]
	v_pk_fma_f32 v[30:31], v[8:9], v[168:169], v[30:31] op_sel_hi:[0,1,1]
	v_pk_fma_f32 v[22:23], v[8:9], v[174:175], v[22:23] op_sel_hi:[0,1,1]
	v_pk_fma_f32 v[8:9], v[8:9], v[172:173], v[26:27] op_sel_hi:[0,1,1]
	v_pk_fma_f32 v[26:27], v[4:5], v[176:177], v[30:31] op_sel_hi:[0,1,1]
	v_pk_fma_f32 v[28:29], v[4:5], v[178:179], v[28:29] op_sel_hi:[0,1,1]
	v_pk_fma_f32 v[30:31], v[4:5], v[180:181], v[8:9] op_sel_hi:[0,1,1]
	v_pk_fma_f32 v[4:5], v[4:5], v[182:183], v[22:23] op_sel_hi:[0,1,1]
	v_pk_fma_f32 v[14:15], v[6:7], v[212:213], v[26:27] op_sel_hi:[0,1,1]
	v_pk_fma_f32 v[8:9], v[6:7], v[214:215], v[28:29] op_sel_hi:[0,1,1]
	v_min_f32_e32 v16, 0, v14
	v_mul_f32_e64 v14, |v14|, s96
	v_exp_f32_e32 v14, v14
	s_waitcnt vmcnt(0)
	v_pk_fma_f32 v[4:5], v[6:7], v[20:21], v[4:5] op_sel_hi:[0,1,1]
	v_pk_fma_f32 v[6:7], v[6:7], v[18:19], v[30:31] op_sel_hi:[0,1,1]
	v_mov_b32_e32 v20, 0
	v_add_f32_e32 v14, 1.0, v14
	v_cmp_gt_f32_e32 vcc, s97, v14
	v_mov_b32_e32 v21, 0
	s_nop 0
	v_cndmask_b32_e64 v17, 0, 32, vcc
	v_ldexp_f32 v14, v14, v17
	v_log_f32_e32 v14, v14
	s_nop 0
	v_mul_f32_e32 v17, 0x3f317217, v14
	v_fma_f32 v17, v14, s92, -v17
	v_fmac_f32_e32 v17, 0x3377d1cf, v14
	v_fmac_f32_e32 v17, 0x3f317217, v14
	v_cmp_lt_f32_e64 s[74:75], |v14|, s8
	s_nop 1
	v_cndmask_b32_e64 v14, v14, v17, s[74:75]
	v_cndmask_b32_e32 v17, 0, v47, vcc
	v_sub_f32_e32 v14, v14, v17
	v_min_f32_e32 v17, 0, v15
	v_mul_f32_e64 v15, |v15|, s96
	v_exp_f32_e32 v15, v15
	s_nop 0
	v_add_f32_e32 v15, 1.0, v15
	v_cmp_gt_f32_e32 vcc, s97, v15
	s_nop 1
	v_cndmask_b32_e64 v18, 0, 32, vcc
	v_ldexp_f32 v15, v15, v18
	v_log_f32_e32 v15, v15
	s_nop 0
	v_mul_f32_e32 v18, 0x3f317217, v15
	v_fma_f32 v18, v15, s92, -v18
	v_fmac_f32_e32 v18, 0x3377d1cf, v15
	v_fmac_f32_e32 v18, 0x3f317217, v15
	v_cmp_lt_f32_e64 s[74:75], |v15|, s8
	s_nop 1
	v_cndmask_b32_e64 v15, v15, v18, s[74:75]
	v_cndmask_b32_e32 v18, 0, v47, vcc
	v_sub_f32_e32 v15, v15, v18
	v_pk_add_f32 v[14:15], v[16:17], v[14:15] neg_lo:[0,1] neg_hi:[0,1]
	v_ashrrev_i32_e32 v17, 6, v82
	v_pk_mul_f32 v[14:15], v[14:15], s[6:7] op_sel_hi:[1,0]
	ds_write2_b32 v13, v14, v15 offset1:1
	v_min_f32_e32 v14, 0, v8
	v_mul_f32_e64 v8, |v8|, s96
	v_exp_f32_e32 v8, v8
	s_nop 0
	v_add_f32_e32 v8, 1.0, v8
	v_cmp_gt_f32_e32 vcc, s97, v8
	s_nop 1
	v_cndmask_b32_e64 v15, 0, 32, vcc
	v_ldexp_f32 v8, v8, v15
	v_log_f32_e32 v8, v8
	s_nop 0
; #define LAS __attribute__((address_space(3)))
; DI float bflo(unsigned w) { return __uint_as_float(w << 16); }
; DI float bfhi(unsigned w) { return __uint_as_float(w & 0xffff0000u); }
; DI void gla_stage1(const Ctx& c0, int layer, int unit, LAS unsigned char* lds) {
;     ...
;     const int cc = tid >> 3, ch = tid & 7;
; #pragma unroll
;     for (int it = 0; it < 2; ++it) { const int idx = tid + 512 * it, vc_ = idx & 15, c_ = idx >> 4;
;         const u32x4 v = *(const u32x4*)(gv + (row0 + c_) * 512 + h * 128 + vc_ * 8);
;         *(LAS u32x4*)(lds + G1_VI + (vc_ >> 2) * 4096 + c_ * 64 + (vc_ & 3) * 16) = v; }
;     {
;         float ga[16];
;         { const u32x4 g0 = *(const u32x4*)(misc + (row0 + cc) * 64 + 32), g1 = *(const u32x4*)(misc + (row0 + cc) * 64 + 40);
;           ga[0] = bflo(g0.x); ga[1] = bfhi(g0.x); ga[2] = bflo(g0.y); ga[3] = bfhi(g0.y); ga[4] = bflo(g0.z); ga[5] = bfhi(g0.z); ga[6] = bflo(g0.w); ga[7] = bfhi(g0.w);
;           ga[8] = bflo(g1.x); ga[9] = bfhi(g1.x); ga[10] = bflo(g1.y); ga[11] = bfhi(g1.y); ga[12] = bflo(g1.z); ga[13] = bfhi(g1.z); ga[14] = bflo(g1.w); ga[15] = bfhi(g1.w); }
;         f32x4 a0 = *(const f32x4*)(ba + 8 * ch), a1 = *(const f32x4*)(ba + 8 * ch + 4);
;         const float* wap = Wa + 8 * ch; asm volatile("" : "+v"(wap));
;     ...
;         for (int j = 0; j < 8; ++j) { const float x = j < 4 ? a0[j & 3] : a1[j & 3];
;             const float ls = fminf(x, 0.f) - __logf(1.f + __expf(-fabsf(x)));
;             LA[cc * 65 + 8 * ch + j] = ls * (1.f / 16.f); }
	v_mul_f32_e32 v15, 0x3f317217, v8
	v_fma_f32 v15, v8, s92, -v15
	v_fmac_f32_e32 v15, 0x3377d1cf, v8
	v_fmac_f32_e32 v15, 0x3f317217, v8
	v_cmp_lt_f32_e64 s[74:75], |v8|, s8
	s_nop 1
	v_cndmask_b32_e64 v8, v8, v15, s[74:75]
	v_cndmask_b32_e32 v15, 0, v47, vcc
	v_sub_f32_e32 v8, v8, v15
	v_min_f32_e32 v15, 0, v9
	v_mul_f32_e64 v9, |v9|, s96
	v_exp_f32_e32 v9, v9
	s_nop 0
	v_add_f32_e32 v9, 1.0, v9
	v_cmp_gt_f32_e32 vcc, s97, v9
	s_nop 1
	v_cndmask_b32_e64 v16, 0, 32, vcc
	v_ldexp_f32 v9, v9, v16
	v_log_f32_e32 v9, v9
	s_nop 0
	v_mul_f32_e32 v16, 0x3f317217, v9
	v_fma_f32 v16, v9, s92, -v16
	v_fmac_f32_e32 v16, 0x3377d1cf, v9
	v_fmac_f32_e32 v16, 0x3f317217, v9
	v_cmp_lt_f32_e64 s[74:75], |v9|, s8
	s_nop 1
	v_cndmask_b32_e64 v9, v9, v16, s[74:75]
	v_cndmask_b32_e32 v16, 0, v47, vcc
	v_sub_f32_e32 v9, v9, v16
	v_pk_add_f32 v[8:9], v[14:15], v[8:9] neg_lo:[0,1] neg_hi:[0,1]
	v_pk_mul_f32 v[8:9], v[8:9], s[6:7] op_sel_hi:[1,0]
	ds_write2_b32 v13, v8, v9 offset0:2 offset1:3
	v_min_f32_e32 v8, 0, v6
	v_mul_f32_e64 v6, |v6|, s96
	v_exp_f32_e32 v6, v6
	s_nop 0
	v_add_f32_e32 v6, 1.0, v6
	v_cmp_gt_f32_e32 vcc, s97, v6
	s_nop 1
	v_cndmask_b32_e64 v9, 0, 32, vcc
	v_ldexp_f32 v6, v6, v9
	v_log_f32_e32 v6, v6
	s_nop 0
	v_mul_f32_e32 v9, 0x3f317217, v6
	v_fma_f32 v9, v6, s92, -v9
	v_fmac_f32_e32 v9, 0x3377d1cf, v6
	v_fmac_f32_e32 v9, 0x3f317217, v6
	v_cmp_lt_f32_e64 s[74:75], |v6|, s8
	s_nop 1
	v_cndmask_b32_e64 v6, v6, v9, s[74:75]
	v_cndmask_b32_e32 v9, 0, v47, vcc
	v_sub_f32_e32 v6, v6, v9
	v_min_f32_e32 v9, 0, v7
	v_mul_f32_e64 v7, |v7|, s96
	v_exp_f32_e32 v7, v7
	s_nop 0
	v_add_f32_e32 v7, 1.0, v7
	v_cmp_gt_f32_e32 vcc, s97, v7
	s_nop 1
	v_cndmask_b32_e64 v14, 0, 32, vcc
	v_ldexp_f32 v7, v7, v14
	v_log_f32_e32 v7, v7
	s_nop 0
	v_mul_f32_e32 v14, 0x3f317217, v7
	v_fma_f32 v14, v7, s92, -v14
	v_fmac_f32_e32 v14, 0x3377d1cf, v7
	v_fmac_f32_e32 v14, 0x3f317217, v7
	v_cmp_lt_f32_e64 s[74:75], |v7|, s8
	s_nop 1
	v_cndmask_b32_e64 v7, v7, v14, s[74:75]
	v_cndmask_b32_e32 v14, 0, v47, vcc
	v_sub_f32_e32 v7, v7, v14
	v_pk_add_f32 v[6:7], v[8:9], v[6:7] neg_lo:[0,1] neg_hi:[0,1]
	v_pk_mul_f32 v[6:7], v[6:7], s[6:7] op_sel_hi:[1,0]
	ds_write2_b32 v13, v6, v7 offset0:4 offset1:5
	v_min_f32_e32 v6, 0, v4
	v_mul_f32_e64 v4, |v4|, s96
	v_exp_f32_e32 v4, v4
	s_nop 0
	v_add_f32_e32 v4, 1.0, v4
	v_cmp_gt_f32_e32 vcc, s97, v4
	s_nop 1
	v_cndmask_b32_e64 v7, 0, 32, vcc
	v_ldexp_f32 v4, v4, v7
	v_log_f32_e32 v4, v4
	s_nop 0
	v_mul_f32_e32 v7, 0x3f317217, v4
	v_fma_f32 v7, v4, s92, -v7
	v_fmac_f32_e32 v7, 0x3377d1cf, v4
	v_fmac_f32_e32 v7, 0x3f317217, v4
	v_cmp_lt_f32_e64 s[74:75], |v4|, s8
	s_nop 1
	v_cndmask_b32_e64 v4, v4, v7, s[74:75]
	v_cndmask_b32_e32 v7, 0, v47, vcc
	v_sub_f32_e32 v4, v4, v7
	v_min_f32_e32 v7, 0, v5
	v_mul_f32_e64 v5, |v5|, s96
	v_exp_f32_e32 v5, v5
	s_nop 0
	v_add_f32_e32 v5, 1.0, v5
	v_cmp_gt_f32_e32 vcc, s97, v5
	s_nop 1
	v_cndmask_b32_e64 v8, 0, 32, vcc
	v_ldexp_f32 v5, v5, v8
	v_log_f32_e32 v5, v5
	s_nop 0
	v_mul_f32_e32 v8, 0x3f317217, v5
	v_fma_f32 v8, v5, s92, -v8
	v_fmac_f32_e32 v8, 0x3377d1cf, v5
	v_fmac_f32_e32 v8, 0x3f317217, v5
	v_cmp_lt_f32_e64 s[74:75], |v5|, s8
	s_nop 1
	v_cndmask_b32_e64 v5, v5, v8, s[74:75]
	v_cndmask_b32_e32 v8, 0, v47, vcc
	v_sub_f32_e32 v5, v5, v8
	v_pk_add_f32 v[4:5], v[6:7], v[4:5] neg_lo:[0,1] neg_hi:[0,1]
	v_cmp_lt_i32_e32 vcc, 0, v17
	v_pk_mul_f32 v[4:5], v[4:5], s[6:7] op_sel_hi:[1,0]
	ds_write2_b32 v13, v4, v5 offset0:6 offset1:7
	v_and_b32_e32 v4, 63, v82
	v_lshl_add_u32 v14, v4, 2, 0
	v_mul_lo_u32 v4, v17, s0
	v_add_u32_e32 v4, v14, v4
	v_mov_b32_e32 v10, v82
	v_mov_b32_e32 v32, v102
	s_waitcnt vmcnt(0) lgkmcnt(0)
	s_branch .Lg1j_l1
.Lg1b_l1:
	s_mov_b64 s[98:99], 0x1000
	s_mov_b64 vcc, 0x1b500000
	v_mov_b32_e32 v82, v151
	v_add_u32_e32 v94, 0x200, v82
	v_ashrrev_i32_e32 v78, 4, v94
	v_ashrrev_i32_e32 v79, 31, v78
	v_and_b32_e32 v102, 7, v82
	s_mov_b64 s[74:75], s[84:85]
	s_mov_b64 s[84:85], s[86:87]
	s_ashr_i32 s74, s82, 8
	s_ashr_i32 s75, s74, 31
	v_and_b32_e32 v88, 15, v82
	v_lshlrev_b32_e32 v48, 4, v88
	v_lshlrev_b32_e32 v3, 4, v82
	v_ashrrev_i32_e32 v8, 4, v82
	v_ashrrev_i32_e32 v9, 31, v8
	v_and_b32_e32 v11, 48, v3
	s_lshl_b32 s0, s82, 6
	s_bfe_u32 s81, s82, 0x20006
	s_lshl_b64 s[86:87], s[74:75], 12
	s_and_b32 s0, s0, 0xfc0
	s_or_b32 s86, s86, s0
	v_lshl_add_u64 v[76:77], s[86:87], 0, v[78:79]
	v_lshlrev_b64 v[74:75], 10, v[76:77]
	s_lshl_b32 s0, s81, 8
	s_add_u32 s74, s84, s0
	s_addc_u32 s75, s85, 0
	v_lshl_add_u64 v[100:101], s[74:75], 0, v[48:49]
	v_lshlrev_b32_e32 v48, 5, v102
	s_mov_b64 s[74:75], 0xf500000
	v_lshl_add_u64 v[6:7], v[100:101], 0, s[74:75]
	v_lshl_add_u64 v[80:81], v[6:7], 0, v[74:75]
	global_load_dwordx4 v[228:231], v[80:81], off
	s_add_u32 s74, s33, s0
	s_addc_u32 s75, s77, 0
	v_lshl_add_u64 v[24:25], s[74:75], 0, v[48:49]
	global_load_dwordx4 v[236:239], v[24:25], off offset:2048
	global_load_dwordx4 v[240:243], v[24:25], off offset:3088
	global_load_dwordx4 v[72:75], v[24:25], off offset:3072
	s_add_u32 s88, s78, s0
	s_addc_u32 s89, s79, 0
	v_lshl_add_u64 v[244:245], v[24:25], 0, s[98:99]
	global_load_dwordx4 v[68:71], v[244:245], off
	v_lshl_add_u64 v[246:247], v[244:245], 0, s[98:99]
	v_lshl_add_u64 v[248:249], v[246:247], 0, s[98:99]
	v_lshlrev_b32_e32 v2, 10, v82
	v_and_b32_e32 v2, 0x3000, v2
	v_add3_u32 v13, 0, v2, v11
	v_lshl_add_u64 v[2:3], s[86:87], 0, v[8:9]
	v_lshlrev_b64 v[2:3], 10, v[2:3]
	v_lshl_add_u64 v[2:3], v[6:7], 0, v[2:3]
	global_load_dwordx4 v[224:227], v[2:3], off
	v_lshl_add_u32 v6, v78, 6, v13
	global_load_dwordx4 v[76:79], v[244:245], off offset:16
	v_lshl_add_u32 v8, v8, 6, v13
	s_waitcnt vmcnt(1)
; #define LAS __attribute__((address_space(3)))
; DI float bflo(unsigned w) { return __uint_as_float(w << 16); }
; DI float bfhi(unsigned w) { return __uint_as_float(w & 0xffff0000u); }
; DI void gla_stage1(const Ctx& c0, int layer, int unit, LAS unsigned char* lds) {
;     ...
;     for (int it = 0; it < 2; ++it) { const int idx = tid + 512 * it, vc_ = idx & 15, c_ = idx >> 4;
;         const u32x4 v = *(const u32x4*)(gv + (row0 + c_) * 512 + h * 128 + vc_ * 8);
;         *(LAS u32x4*)(lds + G1_VI + (vc_ >> 2) * 4096 + c_ * 64 + (vc_ & 3) * 16) = v; }
;     {
;         float ga[16];
;         { const u32x4 g0 = *(const u32x4*)(misc + (row0 + cc) * 64 + 32), g1 = *(const u32x4*)(misc + (row0 + cc) * 64 + 40);
;           ga[0] = bflo(g0.x); ga[1] = bfhi(g0.x); ga[2] = bflo(g0.y); ga[3] = bfhi(g0.y); ga[4] = bflo(g0.z); ga[5] = bfhi(g0.z); ga[6] = bflo(g0.w); ga[7] = bfhi(g0.w);
;           ga[8] = bflo(g1.x); ga[9] = bfhi(g1.x); ga[10] = bflo(g1.y); ga[11] = bfhi(g1.y); ga[12] = bflo(g1.z); ga[13] = bfhi(g1.z); ga[14] = bflo(g1.w); ga[15] = bfhi(g1.w); }
;         f32x4 a0 = *(const f32x4*)(ba + 8 * ch), a1 = *(const f32x4*)(ba + 8 * ch + 4);
;         const float* wap = Wa + 8 * ch; asm volatile("" : "+v"(wap));
; #pragma unroll
;         for (int rr = 0; rr < 16; ++rr) { const f32x4 w0 = *(const f32x4*)(wap + rr * 256), w1 = *(const f32x4*)(wap + rr * 256 + 4); a0 += w0 * ga[rr]; a1 += w1 * ga[rr]; }
	ds_write_b128 v8, v[224:227] offset:43264
	ds_write_b128 v6, v[228:231] offset:43264
	v_ashrrev_i32_e32 v12, 3, v82
	v_ashrrev_i32_e32 v13, 31, v12
	v_lshl_add_u64 v[2:3], s[86:87], 0, v[12:13]
	v_lshlrev_b64 v[4:5], 7, v[2:3]
	v_lshl_add_u64 v[4:5], s[84:85], 0, v[4:5]
	v_lshl_add_u64 v[8:9], v[4:5], 0, vcc
	global_load_dwordx4 v[4:7], v[8:9], off offset:64
	global_load_dwordx4 v[232:235], v[8:9], off offset:80
	s_waitcnt vmcnt(0)
	v_and_b32_e32 v20, 0xffff0000, v232
	v_lshlrev_b32_e32 v18, 16, v233
	v_lshlrev_b32_e32 v22, 16, v232
	v_and_b32_e32 v26, 0xffff0000, v7
	v_lshlrev_b32_e32 v28, 16, v7
	v_and_b32_e32 v30, 0xffff0000, v6
	v_lshlrev_b32_e32 v66, 16, v6
	v_and_b32_e32 v64, 0xffff0000, v5
	v_lshlrev_b32_e32 v62, 16, v5
	v_and_b32_e32 v60, 0xffff0000, v4
	v_lshlrev_b32_e32 v58, 16, v4
	v_pk_fma_f32 v[54:55], v[58:59], v[196:197], v[208:209] op_sel_hi:[0,1,1]
	v_pk_fma_f32 v[54:55], v[60:61], v[142:143], v[54:55] op_sel_hi:[0,1,1]
	v_pk_fma_f32 v[54:55], v[62:63], v[220:221], v[54:55] op_sel_hi:[0,1,1]
	v_pk_fma_f32 v[54:55], v[64:65], v[240:241], v[54:55] op_sel_hi:[0,1,1]
	v_pk_fma_f32 v[54:55], v[66:67], v[76:77], v[54:55] op_sel_hi:[0,1,1]
	v_pk_fma_f32 v[56:57], v[58:59], v[198:199], v[210:211] op_sel_hi:[0,1,1]
	v_pk_fma_f32 v[56:57], v[60:61], v[144:145], v[56:57] op_sel_hi:[0,1,1]
	v_pk_fma_f32 v[56:57], v[62:63], v[222:223], v[56:57] op_sel_hi:[0,1,1]
	v_pk_fma_f32 v[56:57], v[64:65], v[242:243], v[56:57] op_sel_hi:[0,1,1]
	v_pk_fma_f32 v[56:57], v[66:67], v[78:79], v[56:57] op_sel_hi:[0,1,1]
	v_pk_fma_f32 v[56:57], v[30:31], v[98:99], v[56:57] op_sel_hi:[0,1,1]
	v_pk_fma_f32 v[40:41], v[28:29], v[112:113], v[56:57] op_sel_hi:[0,1,1]
	v_pk_fma_f32 v[40:41], v[26:27], v[166:167], v[40:41] op_sel_hi:[0,1,1]
	v_pk_fma_f32 v[42:43], v[58:59], v[200:201], v[204:205] op_sel_hi:[0,1,1]
	v_pk_fma_f32 v[42:43], v[60:61], v[216:217], v[42:43] op_sel_hi:[0,1,1]
	v_pk_fma_f32 v[42:43], v[62:63], v[236:237], v[42:43] op_sel_hi:[0,1,1]
	v_pk_fma_f32 v[42:43], v[64:65], v[72:73], v[42:43] op_sel_hi:[0,1,1]
	v_pk_fma_f32 v[42:43], v[66:67], v[68:69], v[42:43] op_sel_hi:[0,1,1]
	v_pk_fma_f32 v[42:43], v[30:31], v[90:91], v[42:43] op_sel_hi:[0,1,1]
	v_pk_fma_f32 v[42:43], v[28:29], v[106:107], v[42:43] op_sel_hi:[0,1,1]
	v_pk_fma_f32 v[42:43], v[26:27], v[114:115], v[42:43] op_sel_hi:[0,1,1]
	v_pk_fma_f32 v[42:43], v[22:23], v[122:123], v[42:43] op_sel_hi:[0,1,1]
	v_pk_fma_f32 v[44:45], v[58:59], v[202:203], v[206:207] op_sel_hi:[0,1,1]
	v_pk_fma_f32 v[44:45], v[60:61], v[218:219], v[44:45] op_sel_hi:[0,1,1]
	v_pk_fma_f32 v[44:45], v[62:63], v[238:239], v[44:45] op_sel_hi:[0,1,1]
	v_pk_fma_f32 v[44:45], v[64:65], v[74:75], v[44:45] op_sel_hi:[0,1,1]
	v_pk_fma_f32 v[44:45], v[66:67], v[70:71], v[44:45] op_sel_hi:[0,1,1]
	v_pk_fma_f32 v[44:45], v[30:31], v[92:93], v[44:45] op_sel_hi:[0,1,1]
	v_pk_fma_f32 v[30:31], v[30:31], v[96:97], v[54:55] op_sel_hi:[0,1,1]
	v_pk_fma_f32 v[44:45], v[28:29], v[108:109], v[44:45] op_sel_hi:[0,1,1]
	v_pk_fma_f32 v[38:39], v[28:29], v[110:111], v[30:31] op_sel_hi:[0,1,1]
	v_pk_fma_f32 v[30:31], v[26:27], v[116:117], v[44:45] op_sel_hi:[0,1,1]
	v_pk_fma_f32 v[30:31], v[22:23], v[124:125], v[30:31] op_sel_hi:[0,1,1]
	v_pk_fma_f32 v[30:31], v[20:21], v[132:133], v[30:31] op_sel_hi:[0,1,1]
	v_pk_fma_f32 v[38:39], v[26:27], v[164:165], v[38:39] op_sel_hi:[0,1,1]
	v_pk_fma_f32 v[38:39], v[22:23], v[126:127], v[38:39] op_sel_hi:[0,1,1]
	v_pk_fma_f32 v[34:35], v[20:21], v[134:135], v[38:39] op_sel_hi:[0,1,1]
	v_pk_fma_f32 v[22:23], v[22:23], v[128:129], v[40:41] op_sel_hi:[0,1,1]
	v_pk_fma_f32 v[40:41], v[20:21], v[130:131], v[42:43] op_sel_hi:[0,1,1]
	v_pk_fma_f32 v[36:37], v[20:21], v[136:137], v[22:23] op_sel_hi:[0,1,1]
	v_pk_fma_f32 v[38:39], v[18:19], v[138:139], v[40:41] op_sel_hi:[0,1,1]
	v_pk_fma_f32 v[22:23], v[18:19], v[140:141], v[30:31] op_sel_hi:[0,1,1]
	v_pk_fma_f32 v[30:31], v[18:19], v[84:85], v[34:35] op_sel_hi:[0,1,1]
	v_pk_fma_f32 v[34:35], v[18:19], v[86:87], v[36:37] op_sel_hi:[0,1,1]
	global_load_dwordx4 v[18:21], v[248:249], off offset:3088
	s_movk_i32 s0, 0x104
	v_lshl_add_u32 v33, v82, 2, 0
	v_mul_lo_u32 v13, v12, s0
	v_add3_u32 v13, 0, v13, v48
	s_movk_i32 s0, 0x820
	v_and_b32_e32 v16, 0xffff0000, v233
	v_lshlrev_b32_e32 v14, 16, v234
	v_and_b32_e32 v8, 0xffff0000, v234
	v_lshlrev_b32_e32 v4, 16, v235
	v_and_b32_e32 v6, 0xffff0000, v235
	v_lshl_add_u64 v[58:59], v[24:25], 0, s[98:99]
	v_lshl_add_u64 v[44:45], v[58:59], 0, s[98:99]
	v_lshl_add_u64 v[24:25], v[44:45], 0, s[98:99]
	v_pk_fma_f32 v[36:37], v[16:17], v[148:149], v[22:23] op_sel_hi:[0,1,1]
	v_pk_fma_f32 v[38:39], v[16:17], v[146:147], v[38:39] op_sel_hi:[0,1,1]
	v_pk_fma_f32 v[28:29], v[16:17], v[158:159], v[34:35] op_sel_hi:[0,1,1]
	v_pk_fma_f32 v[26:27], v[16:17], v[156:157], v[30:31] op_sel_hi:[0,1,1]
	v_pk_fma_f32 v[30:31], v[14:15], v[160:161], v[38:39] op_sel_hi:[0,1,1]
	v_pk_fma_f32 v[34:35], v[14:15], v[162:163], v[36:37] op_sel_hi:[0,1,1]
	v_pk_fma_f32 v[26:27], v[14:15], v[118:119], v[26:27] op_sel_hi:[0,1,1]
	v_pk_fma_f32 v[22:23], v[14:15], v[120:121], v[28:29] op_sel_hi:[0,1,1]
	v_pk_fma_f32 v[28:29], v[8:9], v[170:171], v[34:35] op_sel_hi:[0,1,1]
	v_pk_fma_f32 v[30:31], v[8:9], v[168:169], v[30:31] op_sel_hi:[0,1,1]
	v_pk_fma_f32 v[22:23], v[8:9], v[174:175], v[22:23] op_sel_hi:[0,1,1]
	v_pk_fma_f32 v[8:9], v[8:9], v[172:173], v[26:27] op_sel_hi:[0,1,1]
	v_pk_fma_f32 v[26:27], v[4:5], v[176:177], v[30:31] op_sel_hi:[0,1,1]
	v_pk_fma_f32 v[28:29], v[4:5], v[178:179], v[28:29] op_sel_hi:[0,1,1]
	v_pk_fma_f32 v[30:31], v[4:5], v[180:181], v[8:9] op_sel_hi:[0,1,1]
	v_pk_fma_f32 v[4:5], v[4:5], v[182:183], v[22:23] op_sel_hi:[0,1,1]
	v_pk_fma_f32 v[14:15], v[6:7], v[212:213], v[26:27] op_sel_hi:[0,1,1]
	v_pk_fma_f32 v[8:9], v[6:7], v[214:215], v[28:29] op_sel_hi:[0,1,1]
	v_min_f32_e32 v16, 0, v14
	v_mul_f32_e64 v14, |v14|, s96
	v_exp_f32_e32 v14, v14
	s_waitcnt vmcnt(0)
; DI void gla_stage1(const Ctx& c0, int layer, int unit, LAS unsigned char* lds) {
;     ...
;         for (int j = 0; j < 8; ++j) { const float x = j < 4 ? a0[j & 3] : a1[j & 3];
;             const float ls = fminf(x, 0.f) - __logf(1.f + __expf(-fabsf(x)));
;             LA[cc * 65 + 8 * ch + j] = ls * (1.f / 16.f); }
;     }
;     __syncthreads();
;     {
;         const int d = tid & 63, part = tid >> 6; float v[8]; float run = 0.f;
; #pragma unroll
;         for (int j = 0; j < 8; ++j) { run += LA[(8 * part + j) * 65 + d]; v[j] = run; }
;         PART[part * 64 + d] = run;
;         __syncthreads();
;         float off = 0.f;
; #pragma unroll
;         for (int p = 0; p < 8; ++p) off += (p < part) ? PART[p * 64 + d] : 0.f;
	v_pk_fma_f32 v[4:5], v[6:7], v[20:21], v[4:5] op_sel_hi:[0,1,1]
	v_pk_fma_f32 v[6:7], v[6:7], v[18:19], v[30:31] op_sel_hi:[0,1,1]
	v_mov_b32_e32 v20, 0
	v_add_f32_e32 v14, 1.0, v14
	v_cmp_gt_f32_e32 vcc, s97, v14
	v_mov_b32_e32 v21, 0
	s_nop 0
	v_cndmask_b32_e64 v17, 0, 32, vcc
	v_ldexp_f32 v14, v14, v17
	v_log_f32_e32 v14, v14
	s_nop 0
	v_mul_f32_e32 v17, 0x3f317217, v14
	v_fma_f32 v17, v14, s92, -v17
	v_fmac_f32_e32 v17, 0x3377d1cf, v14
	v_fmac_f32_e32 v17, 0x3f317217, v14
	v_cmp_lt_f32_e64 s[74:75], |v14|, s8
	s_nop 1
	v_cndmask_b32_e64 v14, v14, v17, s[74:75]
	v_cndmask_b32_e32 v17, 0, v47, vcc
	v_sub_f32_e32 v14, v14, v17
	v_min_f32_e32 v17, 0, v15
	v_mul_f32_e64 v15, |v15|, s96
	v_exp_f32_e32 v15, v15
	s_nop 0
	v_add_f32_e32 v15, 1.0, v15
	v_cmp_gt_f32_e32 vcc, s97, v15
	s_nop 1
	v_cndmask_b32_e64 v18, 0, 32, vcc
	v_ldexp_f32 v15, v15, v18
	v_log_f32_e32 v15, v15
	s_nop 0
	v_mul_f32_e32 v18, 0x3f317217, v15
	v_fma_f32 v18, v15, s92, -v18
	v_fmac_f32_e32 v18, 0x3377d1cf, v15
	v_fmac_f32_e32 v18, 0x3f317217, v15
	v_cmp_lt_f32_e64 s[74:75], |v15|, s8
	s_nop 1
	v_cndmask_b32_e64 v15, v15, v18, s[74:75]
	v_cndmask_b32_e32 v18, 0, v47, vcc
	v_sub_f32_e32 v15, v15, v18
	v_pk_add_f32 v[14:15], v[16:17], v[14:15] neg_lo:[0,1] neg_hi:[0,1]
	v_ashrrev_i32_e32 v17, 6, v82
	v_pk_mul_f32 v[14:15], v[14:15], s[6:7] op_sel_hi:[1,0]
	ds_write2_b32 v13, v14, v15 offset1:1
	v_min_f32_e32 v14, 0, v8
	v_mul_f32_e64 v8, |v8|, s96
	v_exp_f32_e32 v8, v8
	s_nop 0
	v_add_f32_e32 v8, 1.0, v8
	v_cmp_gt_f32_e32 vcc, s97, v8
	s_nop 1
	v_cndmask_b32_e64 v15, 0, 32, vcc
	v_ldexp_f32 v8, v8, v15
	v_log_f32_e32 v8, v8
	s_nop 0
	v_mul_f32_e32 v15, 0x3f317217, v8
	v_fma_f32 v15, v8, s92, -v15
	v_fmac_f32_e32 v15, 0x3377d1cf, v8
	v_fmac_f32_e32 v15, 0x3f317217, v8
	v_cmp_lt_f32_e64 s[74:75], |v8|, s8
	s_nop 1
	v_cndmask_b32_e64 v8, v8, v15, s[74:75]
	v_cndmask_b32_e32 v15, 0, v47, vcc
	v_sub_f32_e32 v8, v8, v15
	v_min_f32_e32 v15, 0, v9
	v_mul_f32_e64 v9, |v9|, s96
	v_exp_f32_e32 v9, v9
	s_nop 0
	v_add_f32_e32 v9, 1.0, v9
	v_cmp_gt_f32_e32 vcc, s97, v9
	s_nop 1
	v_cndmask_b32_e64 v16, 0, 32, vcc
	v_ldexp_f32 v9, v9, v16
	v_log_f32_e32 v9, v9
	s_nop 0
	v_mul_f32_e32 v16, 0x3f317217, v9
	v_fma_f32 v16, v9, s92, -v16
	v_fmac_f32_e32 v16, 0x3377d1cf, v9
	v_fmac_f32_e32 v16, 0x3f317217, v9
	v_cmp_lt_f32_e64 s[74:75], |v9|, s8
	s_nop 1
	v_cndmask_b32_e64 v9, v9, v16, s[74:75]
	v_cndmask_b32_e32 v16, 0, v47, vcc
	v_sub_f32_e32 v9, v9, v16
	v_pk_add_f32 v[8:9], v[14:15], v[8:9] neg_lo:[0,1] neg_hi:[0,1]
	v_pk_mul_f32 v[8:9], v[8:9], s[6:7] op_sel_hi:[1,0]
	ds_write2_b32 v13, v8, v9 offset0:2 offset1:3
	v_min_f32_e32 v8, 0, v6
	v_mul_f32_e64 v6, |v6|, s96
	v_exp_f32_e32 v6, v6
	s_nop 0
	v_add_f32_e32 v6, 1.0, v6
	v_cmp_gt_f32_e32 vcc, s97, v6
	s_nop 1
	v_cndmask_b32_e64 v9, 0, 32, vcc
	v_ldexp_f32 v6, v6, v9
	v_log_f32_e32 v6, v6
	s_nop 0
	v_mul_f32_e32 v9, 0x3f317217, v6
	v_fma_f32 v9, v6, s92, -v9
	v_fmac_f32_e32 v9, 0x3377d1cf, v6
	v_fmac_f32_e32 v9, 0x3f317217, v6
	v_cmp_lt_f32_e64 s[74:75], |v6|, s8
	s_nop 1
	v_cndmask_b32_e64 v6, v6, v9, s[74:75]
	v_cndmask_b32_e32 v9, 0, v47, vcc
	v_sub_f32_e32 v6, v6, v9
	v_min_f32_e32 v9, 0, v7
	v_mul_f32_e64 v7, |v7|, s96
	v_exp_f32_e32 v7, v7
	s_nop 0
	v_add_f32_e32 v7, 1.0, v7
	v_cmp_gt_f32_e32 vcc, s97, v7
	s_nop 1
	v_cndmask_b32_e64 v14, 0, 32, vcc
	v_ldexp_f32 v7, v7, v14
	v_log_f32_e32 v7, v7
	s_nop 0
	v_mul_f32_e32 v14, 0x3f317217, v7
	v_fma_f32 v14, v7, s92, -v14
	v_fmac_f32_e32 v14, 0x3377d1cf, v7
	v_fmac_f32_e32 v14, 0x3f317217, v7
	v_cmp_lt_f32_e64 s[74:75], |v7|, s8
	s_nop 1
	v_cndmask_b32_e64 v7, v7, v14, s[74:75]
	v_cndmask_b32_e32 v14, 0, v47, vcc
	v_sub_f32_e32 v7, v7, v14
	v_pk_add_f32 v[6:7], v[8:9], v[6:7] neg_lo:[0,1] neg_hi:[0,1]
	v_pk_mul_f32 v[6:7], v[6:7], s[6:7] op_sel_hi:[1,0]
	ds_write2_b32 v13, v6, v7 offset0:4 offset1:5
	v_min_f32_e32 v6, 0, v4
	v_mul_f32_e64 v4, |v4|, s96
	v_exp_f32_e32 v4, v4
	s_nop 0
	v_add_f32_e32 v4, 1.0, v4
	v_cmp_gt_f32_e32 vcc, s97, v4
	s_nop 1
	v_cndmask_b32_e64 v7, 0, 32, vcc
	v_ldexp_f32 v4, v4, v7
	v_log_f32_e32 v4, v4
	s_nop 0
	v_mul_f32_e32 v7, 0x3f317217, v4
	v_fma_f32 v7, v4, s92, -v7
	v_fmac_f32_e32 v7, 0x3377d1cf, v4
	v_fmac_f32_e32 v7, 0x3f317217, v4
	v_cmp_lt_f32_e64 s[74:75], |v4|, s8
	s_nop 1
	v_cndmask_b32_e64 v4, v4, v7, s[74:75]
	v_cndmask_b32_e32 v7, 0, v47, vcc
	v_sub_f32_e32 v4, v4, v7
	v_min_f32_e32 v7, 0, v5
	v_mul_f32_e64 v5, |v5|, s96
	v_exp_f32_e32 v5, v5
	s_nop 0
	v_add_f32_e32 v5, 1.0, v5
	v_cmp_gt_f32_e32 vcc, s97, v5
	s_nop 1
	v_cndmask_b32_e64 v8, 0, 32, vcc
	v_ldexp_f32 v5, v5, v8
	v_log_f32_e32 v5, v5
	s_nop 0
	v_mul_f32_e32 v8, 0x3f317217, v5
	v_fma_f32 v8, v5, s92, -v8
	v_fmac_f32_e32 v8, 0x3377d1cf, v5
	v_fmac_f32_e32 v8, 0x3f317217, v5
	v_cmp_lt_f32_e64 s[74:75], |v5|, s8
	s_nop 1
	v_cndmask_b32_e64 v5, v5, v8, s[74:75]
	v_cndmask_b32_e32 v8, 0, v47, vcc
	v_sub_f32_e32 v5, v5, v8
	v_pk_add_f32 v[4:5], v[6:7], v[4:5] neg_lo:[0,1] neg_hi:[0,1]
	v_cmp_lt_i32_e32 vcc, 0, v17
	v_pk_mul_f32 v[4:5], v[4:5], s[6:7] op_sel_hi:[1,0]
	ds_write2_b32 v13, v4, v5 offset0:6 offset1:7
	v_and_b32_e32 v4, 63, v82
	v_lshl_add_u32 v14, v4, 2, 0
	v_mul_lo_u32 v4, v17, s0
	v_add_u32_e32 v4, v14, v4
	v_mov_b32_e32 v10, v82
	v_mov_b32_e32 v32, v102
	s_waitcnt vmcnt(0) lgkmcnt(0)
.Lg1j_l1:
	s_barrier
	ds_read2_b32 v[6:7], v4 offset1:65
	ds_read2_b32 v[8:9], v4 offset0:130 offset1:195
	s_waitcnt lgkmcnt(1)
	v_add_f32_e32 v5, 0, v6
	v_add_f32_e32 v6, v5, v7
	s_waitcnt lgkmcnt(0)
	v_add_f32_e32 v7, v6, v8
	v_add_f32_e32 v8, v7, v9
	v_add_u32_e32 v9, 0x400, v4
	ds_read2_b32 v[18:19], v9 offset0:4 offset1:69
	s_waitcnt lgkmcnt(0)
	v_add_f32_e32 v15, v8, v18
	v_add_f32_e32 v16, v15, v19
	ds_read2_b32 v[18:19], v9 offset0:134 offset1:199
	s_waitcnt lgkmcnt(0)
	v_add_f32_e32 v18, v16, v18
	v_add_f32_e32 v19, v18, v19
	ds_write_b32 v33, v19 offset:16640
	s_waitcnt lgkmcnt(0)
	s_barrier
	s_and_saveexec_b64 s[74:75], vcc
	s_cbranch_execz .LBB0_1018
	ds_read_b32 v21, v14 offset:16640
	s_waitcnt lgkmcnt(0)
	v_add_f32_e32 v21, 0, v21
